# on top of flat release poll: per-segment s_setprio flips deleted from the eight GEMM K-loops (A/B of the role-split priority)
# speedup vs baseline: 1.0072x; 1.0033x over previous
.LBB0_226:
	ds_read_b128 v[156:159], v152
	ds_read_b128 v[160:163], v152 offset:1024
	ds_read_b128 v[164:167], v152 offset:2048
	ds_read_b128 v[168:171], v152 offset:3072
	ds_read_b128 v[172:175], v153
	ds_read_b128 v[176:179], v153 offset:1024
	ds_read_b128 v[180:183], v153 offset:2048
	ds_read_b128 v[186:189], v153 offset:3072
	s_add_u32 s24, s22, 0xfffc0080
	s_addc_u32 s25, s23, -1
	s_cmp_eq_u32 s51, 12
	s_cselect_b32 s27, s15, s25
	s_cselect_b32 s26, s46, s24
	s_cselect_b32 s25, s13, s50
	s_cselect_b32 s24, s47, s49
	v_lshl_add_u64 v[148:149], s[22:23], 0, v[138:139]
	s_add_i32 m0, s21, 0xc000
	ds_read_b128 v[192:195], v154
	ds_read_b128 v[196:199], v154 offset:1024
	ds_read_b128 v[200:203], v154 offset:2048
	ds_read_b128 v[204:207], v154 offset:3072
	ds_read_b128 v[208:211], v154 offset:4096
	ds_read_b128 v[212:215], v154 offset:5120
	ds_read_b128 v[216:219], v154 offset:6144
	ds_read_b128 v[220:223], v154 offset:7168
	global_load_lds_dwordx4 v[148:149], off
	v_lshl_add_u64 v[148:149], s[22:23], 0, v[140:141]
	s_add_i32 m0, s21, 0xe000
	s_nop 0
	global_load_lds_dwordx4 v[148:149], off
	s_waitcnt vmcnt(8)
	s_waitcnt lgkmcnt(0)
	s_barrier
	s_waitcnt lgkmcnt(0)
	v_mfma_f32_16x16x32_bf16 v[124:127], v[156:159], v[192:195], v[124:127]
	v_mfma_f32_16x16x32_bf16 v[120:123], v[164:167], v[192:195], v[120:123]
	v_mfma_f32_16x16x32_bf16 v[112:115], v[156:159], v[200:203], v[112:115]
	v_mfma_f32_16x16x32_bf16 v[104:107], v[164:167], v[200:203], v[104:107]
	v_mfma_f32_16x16x32_bf16 v[96:99], v[156:159], v[208:211], v[96:99]
	v_mfma_f32_16x16x32_bf16 v[88:91], v[164:167], v[208:211], v[88:91]
	v_mfma_f32_16x16x32_bf16 v[80:83], v[156:159], v[216:219], v[80:83]
	v_mfma_f32_16x16x32_bf16 v[72:75], v[164:167], v[216:219], v[72:75]
	v_mfma_f32_16x16x32_bf16 v[124:127], v[160:163], v[196:199], v[124:127]
	v_mfma_f32_16x16x32_bf16 v[120:123], v[168:171], v[196:199], v[120:123]
	v_mfma_f32_16x16x32_bf16 v[112:115], v[160:163], v[204:207], v[112:115]
	v_mfma_f32_16x16x32_bf16 v[104:107], v[168:171], v[204:207], v[104:107]
	v_mfma_f32_16x16x32_bf16 v[96:99], v[160:163], v[212:215], v[96:99]
	v_mfma_f32_16x16x32_bf16 v[88:91], v[168:171], v[212:215], v[88:91]
	v_mfma_f32_16x16x32_bf16 v[80:83], v[160:163], v[220:223], v[80:83]
	v_mfma_f32_16x16x32_bf16 v[72:75], v[168:171], v[220:223], v[72:75]
	v_mfma_f32_16x16x32_bf16 v[116:119], v[172:175], v[192:195], v[116:119]
	v_mfma_f32_16x16x32_bf16 v[108:111], v[180:183], v[192:195], v[108:111]
	v_mfma_f32_16x16x32_bf16 v[100:103], v[172:175], v[200:203], v[100:103]
	v_mfma_f32_16x16x32_bf16 v[92:95], v[180:183], v[200:203], v[92:95]
	v_mfma_f32_16x16x32_bf16 v[84:87], v[172:175], v[208:211], v[84:87]
	v_mfma_f32_16x16x32_bf16 v[76:79], v[180:183], v[208:211], v[76:79]
	v_mfma_f32_16x16x32_bf16 v[68:71], v[172:175], v[216:219], v[68:71]
	v_mfma_f32_16x16x32_bf16 v[64:67], v[180:183], v[216:219], v[64:67]
	v_mfma_f32_16x16x32_bf16 v[116:119], v[176:179], v[196:199], v[116:119]
	v_mfma_f32_16x16x32_bf16 v[108:111], v[186:189], v[196:199], v[108:111]
	v_mfma_f32_16x16x32_bf16 v[100:103], v[176:179], v[204:207], v[100:103]
	v_mfma_f32_16x16x32_bf16 v[92:95], v[186:189], v[204:207], v[92:95]
	v_mfma_f32_16x16x32_bf16 v[84:87], v[176:179], v[212:215], v[84:87]
	v_mfma_f32_16x16x32_bf16 v[76:79], v[186:189], v[212:215], v[76:79]
	v_mfma_f32_16x16x32_bf16 v[68:71], v[176:179], v[220:223], v[68:71]
	v_mfma_f32_16x16x32_bf16 v[64:67], v[186:189], v[220:223], v[64:67]
	s_barrier
	s_add_i32 s52, s41, s30
	v_lshl_add_u64 v[148:149], s[24:25], 0, v[130:131]
	s_mov_b32 m0, s52
	ds_read_b128 v[192:195], v154 offset:16384
	ds_read_b128 v[196:199], v154 offset:17408
	ds_read_b128 v[200:203], v154 offset:18432
	ds_read_b128 v[204:207], v154 offset:19456
	ds_read_b128 v[208:211], v154 offset:20480
	ds_read_b128 v[212:215], v154 offset:21504
	ds_read_b128 v[216:219], v154 offset:22528
	ds_read_b128 v[220:223], v154 offset:23552
	global_load_lds_dwordx4 v[148:149], off
	s_add_i32 m0, s52, 0x2000
	s_add_u32 s52, s24, 0x40000
	v_lshl_add_u64 v[224:225], s[24:25], 0, v[134:135]
	s_addc_u32 s53, s25, 0
	s_add_i32 s54, s42, s30
	global_load_lds_dwordx4 v[224:225], off
	v_lshl_add_u64 v[226:227], s[52:53], 0, v[130:131]
	s_mov_b32 m0, s54
	v_lshl_add_u64 v[228:229], s[26:27], 0, v[132:133]
	global_load_lds_dwordx4 v[226:227], off
	v_lshl_add_u64 v[226:227], s[52:53], 0, v[134:135]
	s_add_i32 m0, s54, 0x2000
	s_nop 0
	global_load_lds_dwordx4 v[226:227], off
	v_lshl_add_u64 v[226:227], s[26:27], 0, v[128:129]
	s_mov_b32 m0, s21
	s_nop 0
	global_load_lds_dwordx4 v[226:227], off
	s_mov_b32 m0, s34
	s_nop 0
	global_load_lds_dwordx4 v[228:229], off
	s_waitcnt vmcnt(8)
	s_waitcnt lgkmcnt(0)
	s_barrier
	s_waitcnt lgkmcnt(0)
	v_mfma_f32_16x16x32_bf16 v[60:63], v[156:159], v[192:195], v[60:63]
	v_mfma_f32_16x16x32_bf16 v[56:59], v[164:167], v[192:195], v[56:59]
	v_mfma_f32_16x16x32_bf16 v[48:51], v[156:159], v[200:203], v[48:51]
	v_mfma_f32_16x16x32_bf16 v[40:43], v[164:167], v[200:203], v[40:43]
	v_mfma_f32_16x16x32_bf16 v[32:35], v[156:159], v[208:211], v[32:35]
	v_mfma_f32_16x16x32_bf16 v[24:27], v[164:167], v[208:211], v[24:27]
	v_mfma_f32_16x16x32_bf16 v[16:19], v[156:159], v[216:219], v[16:19]
	v_mfma_f32_16x16x32_bf16 v[8:11], v[164:167], v[216:219], v[8:11]
	v_mfma_f32_16x16x32_bf16 v[60:63], v[160:163], v[196:199], v[60:63]
	v_mfma_f32_16x16x32_bf16 v[56:59], v[168:171], v[196:199], v[56:59]
	v_mfma_f32_16x16x32_bf16 v[48:51], v[160:163], v[204:207], v[48:51]
	v_mfma_f32_16x16x32_bf16 v[40:43], v[168:171], v[204:207], v[40:43]
	v_mfma_f32_16x16x32_bf16 v[32:35], v[160:163], v[212:215], v[32:35]
	v_mfma_f32_16x16x32_bf16 v[24:27], v[168:171], v[212:215], v[24:27]
	v_mfma_f32_16x16x32_bf16 v[16:19], v[160:163], v[220:223], v[16:19]
	v_mfma_f32_16x16x32_bf16 v[8:11], v[168:171], v[220:223], v[8:11]
	v_mfma_f32_16x16x32_bf16 v[52:55], v[172:175], v[192:195], v[52:55]
	v_mfma_f32_16x16x32_bf16 v[44:47], v[180:183], v[192:195], v[44:47]
	v_mfma_f32_16x16x32_bf16 v[36:39], v[172:175], v[200:203], v[36:39]
	v_mfma_f32_16x16x32_bf16 v[28:31], v[180:183], v[200:203], v[28:31]
	v_mfma_f32_16x16x32_bf16 v[20:23], v[172:175], v[208:211], v[20:23]
	v_mfma_f32_16x16x32_bf16 v[12:15], v[180:183], v[208:211], v[12:15]
	v_mfma_f32_16x16x32_bf16 v[4:7], v[172:175], v[216:219], v[4:7]
	v_mfma_f32_16x16x32_bf16 v[0:3], v[180:183], v[216:219], v[0:3]
	v_mfma_f32_16x16x32_bf16 v[52:55], v[176:179], v[196:199], v[52:55]
	v_mfma_f32_16x16x32_bf16 v[44:47], v[186:189], v[196:199], v[44:47]
	v_mfma_f32_16x16x32_bf16 v[36:39], v[176:179], v[204:207], v[36:39]
	v_mfma_f32_16x16x32_bf16 v[28:31], v[186:189], v[204:207], v[28:31]
	v_mfma_f32_16x16x32_bf16 v[20:23], v[176:179], v[212:215], v[20:23]
	v_mfma_f32_16x16x32_bf16 v[12:15], v[186:189], v[212:215], v[12:15]
	v_mfma_f32_16x16x32_bf16 v[4:7], v[176:179], v[220:223], v[4:7]
	v_mfma_f32_16x16x32_bf16 v[0:3], v[186:189], v[220:223], v[0:3]
	s_barrier
	s_add_i32 s52, 0, 0x18000
	v_add_u32_e32 v136, s52, v150
	s_add_i32 s53, 0, 0x1c000
	ds_read_b128 v[156:159], v136
	ds_read_b128 v[160:163], v136 offset:1024
	ds_read_b128 v[164:167], v136 offset:2048
	ds_read_b128 v[168:171], v136 offset:3072
	v_add_u32_e32 v136, s53, v150
	ds_read_b128 v[172:175], v136
	ds_read_b128 v[176:179], v136 offset:1024
	ds_read_b128 v[180:183], v136 offset:2048
	ds_read_b128 v[186:189], v136 offset:3072
	s_add_u32 s26, s26, 0x40000
	s_addc_u32 s27, s27, 0
	s_mov_b32 m0, s35
	v_lshl_add_u64 v[230:231], s[26:27], 0, v[128:129]
	ds_read_b128 v[192:195], v154 offset:32768
	ds_read_b128 v[196:199], v154 offset:33792
	ds_read_b128 v[200:203], v154 offset:34816
	ds_read_b128 v[204:207], v154 offset:35840
	ds_read_b128 v[208:211], v154 offset:36864
	ds_read_b128 v[212:215], v154 offset:37888
	ds_read_b128 v[216:219], v154 offset:38912
	ds_read_b128 v[220:223], v154 offset:39936
	global_load_lds_dwordx4 v[230:231], off
	v_lshl_add_u64 v[230:231], s[26:27], 0, v[132:133]
	s_mov_b32 m0, s36
	s_nop 0
	global_load_lds_dwordx4 v[230:231], off
	s_waitcnt vmcnt(8)
	s_waitcnt lgkmcnt(0)
	s_barrier
	s_waitcnt lgkmcnt(0)
	v_mfma_f32_16x16x32_bf16 v[124:127], v[156:159], v[192:195], v[124:127]
	v_mfma_f32_16x16x32_bf16 v[120:123], v[164:167], v[192:195], v[120:123]
	v_mfma_f32_16x16x32_bf16 v[112:115], v[156:159], v[200:203], v[112:115]
	v_mfma_f32_16x16x32_bf16 v[104:107], v[164:167], v[200:203], v[104:107]
	v_mfma_f32_16x16x32_bf16 v[96:99], v[156:159], v[208:211], v[96:99]
	v_mfma_f32_16x16x32_bf16 v[88:91], v[164:167], v[208:211], v[88:91]
	v_mfma_f32_16x16x32_bf16 v[80:83], v[156:159], v[216:219], v[80:83]
	v_mfma_f32_16x16x32_bf16 v[72:75], v[164:167], v[216:219], v[72:75]
	v_mfma_f32_16x16x32_bf16 v[124:127], v[160:163], v[196:199], v[124:127]
	v_mfma_f32_16x16x32_bf16 v[120:123], v[168:171], v[196:199], v[120:123]
	v_mfma_f32_16x16x32_bf16 v[112:115], v[160:163], v[204:207], v[112:115]
	v_mfma_f32_16x16x32_bf16 v[104:107], v[168:171], v[204:207], v[104:107]
	v_mfma_f32_16x16x32_bf16 v[96:99], v[160:163], v[212:215], v[96:99]
	v_mfma_f32_16x16x32_bf16 v[88:91], v[168:171], v[212:215], v[88:91]
	v_mfma_f32_16x16x32_bf16 v[80:83], v[160:163], v[220:223], v[80:83]
	v_mfma_f32_16x16x32_bf16 v[72:75], v[168:171], v[220:223], v[72:75]
	v_mfma_f32_16x16x32_bf16 v[116:119], v[172:175], v[192:195], v[116:119]
	v_mfma_f32_16x16x32_bf16 v[108:111], v[180:183], v[192:195], v[108:111]
	v_mfma_f32_16x16x32_bf16 v[100:103], v[172:175], v[200:203], v[100:103]
	v_mfma_f32_16x16x32_bf16 v[92:95], v[180:183], v[200:203], v[92:95]
	v_mfma_f32_16x16x32_bf16 v[84:87], v[172:175], v[208:211], v[84:87]
	v_mfma_f32_16x16x32_bf16 v[76:79], v[180:183], v[208:211], v[76:79]
	v_mfma_f32_16x16x32_bf16 v[68:71], v[172:175], v[216:219], v[68:71]
	v_mfma_f32_16x16x32_bf16 v[64:67], v[180:183], v[216:219], v[64:67]
	v_mfma_f32_16x16x32_bf16 v[116:119], v[176:179], v[196:199], v[116:119]
	v_mfma_f32_16x16x32_bf16 v[108:111], v[186:189], v[196:199], v[108:111]
	v_mfma_f32_16x16x32_bf16 v[100:103], v[176:179], v[204:207], v[100:103]
	v_mfma_f32_16x16x32_bf16 v[92:95], v[186:189], v[204:207], v[92:95]
	v_mfma_f32_16x16x32_bf16 v[84:87], v[176:179], v[212:215], v[84:87]
	v_mfma_f32_16x16x32_bf16 v[76:79], v[186:189], v[212:215], v[76:79]
	v_mfma_f32_16x16x32_bf16 v[68:71], v[176:179], v[220:223], v[68:71]
	v_mfma_f32_16x16x32_bf16 v[64:67], v[186:189], v[220:223], v[64:67]
	s_barrier
	s_add_i32 s26, s52, s30
	v_lshl_add_u64 v[148:149], v[148:149], 0, s[6:7]
	s_mov_b32 m0, s26
	ds_read_b128 v[192:195], v154 offset:49152
	ds_read_b128 v[196:199], v154 offset:50176
	ds_read_b128 v[200:203], v154 offset:51200
	ds_read_b128 v[204:207], v154 offset:52224
	ds_read_b128 v[208:211], v154 offset:53248
	ds_read_b128 v[212:215], v154 offset:54272
	ds_read_b128 v[216:219], v154 offset:55296
	ds_read_b128 v[220:223], v154 offset:56320
	global_load_lds_dwordx4 v[148:149], off
	s_add_i32 m0, s26, 0x2000
	s_add_u32 s24, s24, 0x40080
	v_lshl_add_u64 v[148:149], v[224:225], 0, s[6:7]
	s_addc_u32 s25, s25, 0
	s_add_i32 s26, s53, s30
	global_load_lds_dwordx4 v[148:149], off
	v_lshl_add_u64 v[148:149], s[24:25], 0, v[130:131]
	s_mov_b32 m0, s26
	s_nop 0
	global_load_lds_dwordx4 v[148:149], off
	v_lshl_add_u64 v[148:149], s[24:25], 0, v[134:135]
	s_add_i32 m0, s26, 0x2000
	s_nop 0
	global_load_lds_dwordx4 v[148:149], off
	v_lshl_add_u64 v[148:149], v[226:227], 0, s[6:7]
	s_mov_b32 m0, s39
	s_nop 0
	global_load_lds_dwordx4 v[148:149], off
	v_lshl_add_u64 v[148:149], v[228:229], 0, s[6:7]
	s_mov_b32 m0, s40
	s_nop 0
	global_load_lds_dwordx4 v[148:149], off
	s_waitcnt vmcnt(8)
	s_waitcnt lgkmcnt(0)
	s_barrier
	s_waitcnt lgkmcnt(0)
	v_mfma_f32_16x16x32_bf16 v[60:63], v[156:159], v[192:195], v[60:63]
	v_mfma_f32_16x16x32_bf16 v[56:59], v[164:167], v[192:195], v[56:59]
	v_mfma_f32_16x16x32_bf16 v[48:51], v[156:159], v[200:203], v[48:51]
	v_mfma_f32_16x16x32_bf16 v[40:43], v[164:167], v[200:203], v[40:43]
	v_mfma_f32_16x16x32_bf16 v[32:35], v[156:159], v[208:211], v[32:35]
	v_mfma_f32_16x16x32_bf16 v[24:27], v[164:167], v[208:211], v[24:27]
	v_mfma_f32_16x16x32_bf16 v[16:19], v[156:159], v[216:219], v[16:19]
	v_mfma_f32_16x16x32_bf16 v[8:11], v[164:167], v[216:219], v[8:11]
	v_mfma_f32_16x16x32_bf16 v[60:63], v[160:163], v[196:199], v[60:63]
	v_mfma_f32_16x16x32_bf16 v[56:59], v[168:171], v[196:199], v[56:59]
	v_mfma_f32_16x16x32_bf16 v[48:51], v[160:163], v[204:207], v[48:51]
	v_mfma_f32_16x16x32_bf16 v[40:43], v[168:171], v[204:207], v[40:43]
	v_mfma_f32_16x16x32_bf16 v[32:35], v[160:163], v[212:215], v[32:35]
	v_mfma_f32_16x16x32_bf16 v[24:27], v[168:171], v[212:215], v[24:27]
	v_mfma_f32_16x16x32_bf16 v[16:19], v[160:163], v[220:223], v[16:19]
	v_mfma_f32_16x16x32_bf16 v[8:11], v[168:171], v[220:223], v[8:11]
	v_mfma_f32_16x16x32_bf16 v[52:55], v[172:175], v[192:195], v[52:55]
	v_mfma_f32_16x16x32_bf16 v[44:47], v[180:183], v[192:195], v[44:47]
	v_mfma_f32_16x16x32_bf16 v[36:39], v[172:175], v[200:203], v[36:39]
	v_mfma_f32_16x16x32_bf16 v[28:31], v[180:183], v[200:203], v[28:31]
	v_mfma_f32_16x16x32_bf16 v[20:23], v[172:175], v[208:211], v[20:23]
	v_mfma_f32_16x16x32_bf16 v[12:15], v[180:183], v[208:211], v[12:15]
	v_mfma_f32_16x16x32_bf16 v[4:7], v[172:175], v[216:219], v[4:7]
	v_mfma_f32_16x16x32_bf16 v[0:3], v[180:183], v[216:219], v[0:3]
	v_mfma_f32_16x16x32_bf16 v[52:55], v[176:179], v[196:199], v[52:55]
	v_mfma_f32_16x16x32_bf16 v[44:47], v[186:189], v[196:199], v[44:47]
	v_mfma_f32_16x16x32_bf16 v[36:39], v[176:179], v[204:207], v[36:39]
	v_mfma_f32_16x16x32_bf16 v[28:31], v[186:189], v[204:207], v[28:31]
	v_mfma_f32_16x16x32_bf16 v[20:23], v[176:179], v[212:215], v[20:23]
	v_mfma_f32_16x16x32_bf16 v[12:15], v[186:189], v[212:215], v[12:15]
	v_mfma_f32_16x16x32_bf16 v[4:7], v[176:179], v[220:223], v[4:7]
	v_mfma_f32_16x16x32_bf16 v[0:3], v[186:189], v[220:223], v[0:3]
	s_barrier
	s_add_i32 s51, s51, 2
	s_add_u32 s22, s22, 0x100
	s_addc_u32 s23, s23, 0
	s_add_u32 s49, s49, 0x100
	s_addc_u32 s50, s50, 0
	s_cmp_gt_u32 s51, 13
	s_cbranch_scc0 .LBB0_226
	s_and_b64 vcc, exec, s[8:9]
	s_cbranch_vccz .LBB0_229
	s_barrier

.LBB0_380:
	ds_read_b128 v[76:79], v188
	ds_read_b128 v[84:87], v188 offset:1024
	ds_read_b128 v[88:91], v188 offset:2048
	ds_read_b128 v[96:99], v188 offset:3072
	ds_read_b128 v[144:147], v189
	ds_read_b128 v[148:151], v189 offset:1024
	ds_read_b128 v[152:155], v189 offset:2048
	ds_read_b128 v[156:159], v189 offset:3072
	s_add_u32 s28, s26, 0xfffc0080
	s_addc_u32 s29, s27, -1
	s_cmp_eq_u32 s53, 12
	s_cselect_b32 s31, s17, s29
	s_cselect_b32 s30, s23, s28
	s_cselect_b32 s29, s15, s52
	s_cselect_b32 s28, s50, s51
	v_lshl_add_u64 v[214:215], s[26:27], 0, v[164:165]
	s_add_i32 m0, s25, 0xc000
	ds_read_b128 v[172:175], v191
	ds_read_b128 v[176:179], v191 offset:1024
	ds_read_b128 v[180:183], v191 offset:2048
	ds_read_b128 v[194:197], v191 offset:3072
	ds_read_b128 v[198:201], v191 offset:4096
	ds_read_b128 v[202:205], v191 offset:5120
	ds_read_b128 v[206:209], v191 offset:6144
	ds_read_b128 v[210:213], v191 offset:7168
	global_load_lds_dwordx4 v[214:215], off
	v_lshl_add_u64 v[214:215], s[26:27], 0, v[166:167]
	s_add_i32 m0, s25, 0xe000
	s_nop 0
	global_load_lds_dwordx4 v[214:215], off
	s_waitcnt vmcnt(8)
	s_waitcnt lgkmcnt(0)
	s_barrier
	s_waitcnt lgkmcnt(0)
	v_mfma_f32_16x16x32_bf16 v[140:143], v[76:79], v[172:175], v[140:143]
	v_mfma_f32_16x16x32_bf16 v[136:139], v[88:91], v[172:175], v[136:139]
	v_mfma_f32_16x16x32_bf16 v[124:127], v[76:79], v[180:183], v[124:127]
	v_mfma_f32_16x16x32_bf16 v[120:123], v[88:91], v[180:183], v[120:123]
	v_mfma_f32_16x16x32_bf16 v[108:111], v[76:79], v[198:201], v[108:111]
	v_mfma_f32_16x16x32_bf16 v[104:107], v[88:91], v[198:201], v[104:107]
	v_mfma_f32_16x16x32_bf16 v[80:83], v[76:79], v[206:209], v[80:83]
	v_mfma_f32_16x16x32_bf16 v[72:75], v[88:91], v[206:209], v[72:75]
	v_mfma_f32_16x16x32_bf16 v[140:143], v[84:87], v[176:179], v[140:143]
	v_mfma_f32_16x16x32_bf16 v[136:139], v[96:99], v[176:179], v[136:139]
	v_mfma_f32_16x16x32_bf16 v[124:127], v[84:87], v[194:197], v[124:127]
	v_mfma_f32_16x16x32_bf16 v[120:123], v[96:99], v[194:197], v[120:123]
	v_mfma_f32_16x16x32_bf16 v[108:111], v[84:87], v[202:205], v[108:111]
	v_mfma_f32_16x16x32_bf16 v[104:107], v[96:99], v[202:205], v[104:107]
	v_mfma_f32_16x16x32_bf16 v[80:83], v[84:87], v[210:213], v[80:83]
	v_mfma_f32_16x16x32_bf16 v[72:75], v[96:99], v[210:213], v[72:75]
	v_mfma_f32_16x16x32_bf16 v[132:135], v[144:147], v[172:175], v[132:135]
	v_mfma_f32_16x16x32_bf16 v[128:131], v[152:155], v[172:175], v[128:131]
	v_mfma_f32_16x16x32_bf16 v[116:119], v[144:147], v[180:183], v[116:119]
	v_mfma_f32_16x16x32_bf16 v[112:115], v[152:155], v[180:183], v[112:115]
	v_mfma_f32_16x16x32_bf16 v[100:103], v[144:147], v[198:201], v[100:103]
	v_mfma_f32_16x16x32_bf16 v[92:95], v[152:155], v[198:201], v[92:95]
	v_mfma_f32_16x16x32_bf16 v[68:71], v[144:147], v[206:209], v[68:71]
	v_mfma_f32_16x16x32_bf16 v[64:67], v[152:155], v[206:209], v[64:67]
	v_mfma_f32_16x16x32_bf16 v[132:135], v[148:151], v[176:179], v[132:135]
	v_mfma_f32_16x16x32_bf16 v[128:131], v[156:159], v[176:179], v[128:131]
	v_mfma_f32_16x16x32_bf16 v[116:119], v[148:151], v[194:197], v[116:119]
	v_mfma_f32_16x16x32_bf16 v[112:115], v[156:159], v[194:197], v[112:115]
	v_mfma_f32_16x16x32_bf16 v[100:103], v[148:151], v[202:205], v[100:103]
	v_mfma_f32_16x16x32_bf16 v[92:95], v[156:159], v[202:205], v[92:95]
	v_mfma_f32_16x16x32_bf16 v[68:71], v[148:151], v[210:213], v[68:71]
	v_mfma_f32_16x16x32_bf16 v[64:67], v[156:159], v[210:213], v[64:67]
	s_barrier
	s_add_i32 s54, s48, s35
	v_lshl_add_u64 v[214:215], s[28:29], 0, v[160:161]
	s_mov_b32 m0, s54
	ds_read_b128 v[172:175], v191 offset:16384
	ds_read_b128 v[176:179], v191 offset:17408
	ds_read_b128 v[180:183], v191 offset:18432
	ds_read_b128 v[194:197], v191 offset:19456
	ds_read_b128 v[198:201], v191 offset:20480
	ds_read_b128 v[202:205], v191 offset:21504
	ds_read_b128 v[206:209], v191 offset:22528
	ds_read_b128 v[210:213], v191 offset:23552
	global_load_lds_dwordx4 v[214:215], off
	s_add_i32 m0, s54, 0x2000
	s_add_u32 s54, s28, 0x40000
	v_lshl_add_u64 v[216:217], s[28:29], 0, v[162:163]
	s_addc_u32 s55, s29, 0
	s_add_i32 s56, s49, s35
	global_load_lds_dwordx4 v[216:217], off
	v_lshl_add_u64 v[218:219], s[54:55], 0, v[160:161]
	s_mov_b32 m0, s56
	v_lshl_add_u64 v[220:221], s[30:31], 0, v[162:163]
	global_load_lds_dwordx4 v[218:219], off
	v_lshl_add_u64 v[218:219], s[54:55], 0, v[162:163]
	s_add_i32 m0, s56, 0x2000
	s_nop 0
	global_load_lds_dwordx4 v[218:219], off
	v_lshl_add_u64 v[218:219], s[30:31], 0, v[160:161]
	s_mov_b32 m0, s25
	s_nop 0
	global_load_lds_dwordx4 v[218:219], off
	s_mov_b32 m0, s36
	s_nop 0
	global_load_lds_dwordx4 v[220:221], off
	s_waitcnt vmcnt(8)
	s_waitcnt lgkmcnt(0)
	s_barrier
	s_waitcnt lgkmcnt(0)
	v_mfma_f32_16x16x32_bf16 v[60:63], v[76:79], v[172:175], v[60:63]
	v_mfma_f32_16x16x32_bf16 v[56:59], v[88:91], v[172:175], v[56:59]
	v_mfma_f32_16x16x32_bf16 v[44:47], v[76:79], v[180:183], v[44:47]
	v_mfma_f32_16x16x32_bf16 v[40:43], v[88:91], v[180:183], v[40:43]
	v_mfma_f32_16x16x32_bf16 v[28:31], v[76:79], v[198:201], v[28:31]
	v_mfma_f32_16x16x32_bf16 v[24:27], v[88:91], v[198:201], v[24:27]
	v_mfma_f32_16x16x32_bf16 v[12:15], v[76:79], v[206:209], v[12:15]
	v_mfma_f32_16x16x32_bf16 v[8:11], v[88:91], v[206:209], v[8:11]
	v_mfma_f32_16x16x32_bf16 v[60:63], v[84:87], v[176:179], v[60:63]
	v_mfma_f32_16x16x32_bf16 v[56:59], v[96:99], v[176:179], v[56:59]
	v_mfma_f32_16x16x32_bf16 v[44:47], v[84:87], v[194:197], v[44:47]
	v_mfma_f32_16x16x32_bf16 v[40:43], v[96:99], v[194:197], v[40:43]
	v_mfma_f32_16x16x32_bf16 v[28:31], v[84:87], v[202:205], v[28:31]
	v_mfma_f32_16x16x32_bf16 v[24:27], v[96:99], v[202:205], v[24:27]
	v_mfma_f32_16x16x32_bf16 v[12:15], v[84:87], v[210:213], v[12:15]
	v_mfma_f32_16x16x32_bf16 v[8:11], v[96:99], v[210:213], v[8:11]
	v_mfma_f32_16x16x32_bf16 v[52:55], v[144:147], v[172:175], v[52:55]
	v_mfma_f32_16x16x32_bf16 v[48:51], v[152:155], v[172:175], v[48:51]
	v_mfma_f32_16x16x32_bf16 v[36:39], v[144:147], v[180:183], v[36:39]
	v_mfma_f32_16x16x32_bf16 v[32:35], v[152:155], v[180:183], v[32:35]
	v_mfma_f32_16x16x32_bf16 v[20:23], v[144:147], v[198:201], v[20:23]
	v_mfma_f32_16x16x32_bf16 v[16:19], v[152:155], v[198:201], v[16:19]
	v_mfma_f32_16x16x32_bf16 v[4:7], v[144:147], v[206:209], v[4:7]
	v_mfma_f32_16x16x32_bf16 v[0:3], v[152:155], v[206:209], v[0:3]
	v_mfma_f32_16x16x32_bf16 v[52:55], v[148:151], v[176:179], v[52:55]
	v_mfma_f32_16x16x32_bf16 v[48:51], v[156:159], v[176:179], v[48:51]
	v_mfma_f32_16x16x32_bf16 v[36:39], v[148:151], v[194:197], v[36:39]
	v_mfma_f32_16x16x32_bf16 v[32:35], v[156:159], v[194:197], v[32:35]
	v_mfma_f32_16x16x32_bf16 v[20:23], v[148:151], v[202:205], v[20:23]
	v_mfma_f32_16x16x32_bf16 v[16:19], v[156:159], v[202:205], v[16:19]
	v_mfma_f32_16x16x32_bf16 v[4:7], v[148:151], v[210:213], v[4:7]
	v_mfma_f32_16x16x32_bf16 v[0:3], v[156:159], v[210:213], v[0:3]
	s_barrier
	s_add_i32 s54, 0, 0x18000
	s_add_i32 s55, 0, 0x1c000
	v_add_u32_e32 v96, s54, v186
	v_add_u32_e32 v156, s55, v186
	ds_read_b128 v[76:79], v96
	ds_read_b128 v[84:87], v96 offset:1024
	ds_read_b128 v[88:91], v96 offset:2048
	ds_read_b128 v[96:99], v96 offset:3072
	ds_read_b128 v[144:147], v156
	ds_read_b128 v[148:151], v156 offset:1024
	ds_read_b128 v[152:155], v156 offset:2048
	ds_read_b128 v[156:159], v156 offset:3072
	s_add_u32 s30, s30, 0x40000
	s_addc_u32 s31, s31, 0
	s_mov_b32 m0, s37
	v_lshl_add_u64 v[222:223], s[30:31], 0, v[160:161]
	ds_read_b128 v[172:175], v191 offset:32768
	ds_read_b128 v[176:179], v191 offset:33792
	ds_read_b128 v[180:183], v191 offset:34816
	ds_read_b128 v[194:197], v191 offset:35840
	ds_read_b128 v[198:201], v191 offset:36864
	ds_read_b128 v[202:205], v191 offset:37888
	ds_read_b128 v[206:209], v191 offset:38912
	ds_read_b128 v[210:213], v191 offset:39936
	global_load_lds_dwordx4 v[222:223], off
	v_lshl_add_u64 v[222:223], s[30:31], 0, v[162:163]
	s_mov_b32 m0, s38
	s_nop 0
	global_load_lds_dwordx4 v[222:223], off
	s_waitcnt vmcnt(8)
	s_waitcnt lgkmcnt(0)
	s_barrier
	s_waitcnt lgkmcnt(0)
	v_mfma_f32_16x16x32_bf16 v[140:143], v[76:79], v[172:175], v[140:143]
	v_mfma_f32_16x16x32_bf16 v[136:139], v[88:91], v[172:175], v[136:139]
	v_mfma_f32_16x16x32_bf16 v[124:127], v[76:79], v[180:183], v[124:127]
	v_mfma_f32_16x16x32_bf16 v[120:123], v[88:91], v[180:183], v[120:123]
	v_mfma_f32_16x16x32_bf16 v[108:111], v[76:79], v[198:201], v[108:111]
	v_mfma_f32_16x16x32_bf16 v[104:107], v[88:91], v[198:201], v[104:107]
	v_mfma_f32_16x16x32_bf16 v[80:83], v[76:79], v[206:209], v[80:83]
	v_mfma_f32_16x16x32_bf16 v[72:75], v[88:91], v[206:209], v[72:75]
	v_mfma_f32_16x16x32_bf16 v[140:143], v[84:87], v[176:179], v[140:143]
	v_mfma_f32_16x16x32_bf16 v[136:139], v[96:99], v[176:179], v[136:139]
	v_mfma_f32_16x16x32_bf16 v[124:127], v[84:87], v[194:197], v[124:127]
	v_mfma_f32_16x16x32_bf16 v[120:123], v[96:99], v[194:197], v[120:123]
	v_mfma_f32_16x16x32_bf16 v[108:111], v[84:87], v[202:205], v[108:111]
	v_mfma_f32_16x16x32_bf16 v[104:107], v[96:99], v[202:205], v[104:107]
	v_mfma_f32_16x16x32_bf16 v[80:83], v[84:87], v[210:213], v[80:83]
	v_mfma_f32_16x16x32_bf16 v[72:75], v[96:99], v[210:213], v[72:75]
	v_mfma_f32_16x16x32_bf16 v[132:135], v[144:147], v[172:175], v[132:135]
	v_mfma_f32_16x16x32_bf16 v[128:131], v[152:155], v[172:175], v[128:131]
	v_mfma_f32_16x16x32_bf16 v[116:119], v[144:147], v[180:183], v[116:119]
	v_mfma_f32_16x16x32_bf16 v[112:115], v[152:155], v[180:183], v[112:115]
	v_mfma_f32_16x16x32_bf16 v[100:103], v[144:147], v[198:201], v[100:103]
	v_mfma_f32_16x16x32_bf16 v[92:95], v[152:155], v[198:201], v[92:95]
	v_mfma_f32_16x16x32_bf16 v[68:71], v[144:147], v[206:209], v[68:71]
	v_mfma_f32_16x16x32_bf16 v[64:67], v[152:155], v[206:209], v[64:67]
	v_mfma_f32_16x16x32_bf16 v[132:135], v[148:151], v[176:179], v[132:135]
	v_mfma_f32_16x16x32_bf16 v[128:131], v[156:159], v[176:179], v[128:131]
	v_mfma_f32_16x16x32_bf16 v[116:119], v[148:151], v[194:197], v[116:119]
	v_mfma_f32_16x16x32_bf16 v[112:115], v[156:159], v[194:197], v[112:115]
	v_mfma_f32_16x16x32_bf16 v[100:103], v[148:151], v[202:205], v[100:103]
	v_mfma_f32_16x16x32_bf16 v[92:95], v[156:159], v[202:205], v[92:95]
	v_mfma_f32_16x16x32_bf16 v[68:71], v[148:151], v[210:213], v[68:71]
	v_mfma_f32_16x16x32_bf16 v[64:67], v[156:159], v[210:213], v[64:67]
	s_barrier
	s_add_i32 s30, s54, s35
	v_lshl_add_u64 v[214:215], v[214:215], 0, s[10:11]
	s_mov_b32 m0, s30
	ds_read_b128 v[172:175], v191 offset:49152
	ds_read_b128 v[176:179], v191 offset:50176
	ds_read_b128 v[180:183], v191 offset:51200
	ds_read_b128 v[194:197], v191 offset:52224
	ds_read_b128 v[198:201], v191 offset:53248
	ds_read_b128 v[202:205], v191 offset:54272
	ds_read_b128 v[206:209], v191 offset:55296
	ds_read_b128 v[210:213], v191 offset:56320
	global_load_lds_dwordx4 v[214:215], off
	s_add_i32 m0, s30, 0x2000
	s_add_u32 s28, s28, 0x40080
	v_lshl_add_u64 v[214:215], v[216:217], 0, s[10:11]
	s_addc_u32 s29, s29, 0
	s_add_i32 s30, s55, s35
	global_load_lds_dwordx4 v[214:215], off
	v_lshl_add_u64 v[214:215], s[28:29], 0, v[160:161]
	s_mov_b32 m0, s30
	s_nop 0
	global_load_lds_dwordx4 v[214:215], off
	v_lshl_add_u64 v[214:215], s[28:29], 0, v[162:163]
	s_add_i32 m0, s30, 0x2000
	s_nop 0
	global_load_lds_dwordx4 v[214:215], off
	v_lshl_add_u64 v[214:215], v[218:219], 0, s[10:11]
	s_mov_b32 m0, s46
	s_nop 0
	global_load_lds_dwordx4 v[214:215], off
	v_lshl_add_u64 v[214:215], v[220:221], 0, s[10:11]
	s_mov_b32 m0, s47
	s_nop 0
	global_load_lds_dwordx4 v[214:215], off
	s_waitcnt vmcnt(8)
	s_waitcnt lgkmcnt(0)
	s_barrier
	s_waitcnt lgkmcnt(0)
	v_mfma_f32_16x16x32_bf16 v[60:63], v[76:79], v[172:175], v[60:63]
	v_mfma_f32_16x16x32_bf16 v[56:59], v[88:91], v[172:175], v[56:59]
	v_mfma_f32_16x16x32_bf16 v[44:47], v[76:79], v[180:183], v[44:47]
	v_mfma_f32_16x16x32_bf16 v[40:43], v[88:91], v[180:183], v[40:43]
	v_mfma_f32_16x16x32_bf16 v[28:31], v[76:79], v[198:201], v[28:31]
	v_mfma_f32_16x16x32_bf16 v[24:27], v[88:91], v[198:201], v[24:27]
	v_mfma_f32_16x16x32_bf16 v[12:15], v[76:79], v[206:209], v[12:15]
	v_mfma_f32_16x16x32_bf16 v[8:11], v[88:91], v[206:209], v[8:11]
	v_mfma_f32_16x16x32_bf16 v[60:63], v[84:87], v[176:179], v[60:63]
	v_mfma_f32_16x16x32_bf16 v[56:59], v[96:99], v[176:179], v[56:59]
	v_mfma_f32_16x16x32_bf16 v[44:47], v[84:87], v[194:197], v[44:47]
	v_mfma_f32_16x16x32_bf16 v[40:43], v[96:99], v[194:197], v[40:43]
	v_mfma_f32_16x16x32_bf16 v[28:31], v[84:87], v[202:205], v[28:31]
	v_mfma_f32_16x16x32_bf16 v[24:27], v[96:99], v[202:205], v[24:27]
	v_mfma_f32_16x16x32_bf16 v[12:15], v[84:87], v[210:213], v[12:15]
	v_mfma_f32_16x16x32_bf16 v[8:11], v[96:99], v[210:213], v[8:11]
	v_mfma_f32_16x16x32_bf16 v[52:55], v[144:147], v[172:175], v[52:55]
	v_mfma_f32_16x16x32_bf16 v[48:51], v[152:155], v[172:175], v[48:51]
	v_mfma_f32_16x16x32_bf16 v[36:39], v[144:147], v[180:183], v[36:39]
	v_mfma_f32_16x16x32_bf16 v[32:35], v[152:155], v[180:183], v[32:35]
	v_mfma_f32_16x16x32_bf16 v[20:23], v[144:147], v[198:201], v[20:23]
	v_mfma_f32_16x16x32_bf16 v[16:19], v[152:155], v[198:201], v[16:19]
	v_mfma_f32_16x16x32_bf16 v[4:7], v[144:147], v[206:209], v[4:7]
	v_mfma_f32_16x16x32_bf16 v[0:3], v[152:155], v[206:209], v[0:3]
	v_mfma_f32_16x16x32_bf16 v[52:55], v[148:151], v[176:179], v[52:55]
	v_mfma_f32_16x16x32_bf16 v[48:51], v[156:159], v[176:179], v[48:51]
	v_mfma_f32_16x16x32_bf16 v[36:39], v[148:151], v[194:197], v[36:39]
	v_mfma_f32_16x16x32_bf16 v[32:35], v[156:159], v[194:197], v[32:35]
	v_mfma_f32_16x16x32_bf16 v[20:23], v[148:151], v[202:205], v[20:23]
	v_mfma_f32_16x16x32_bf16 v[16:19], v[156:159], v[202:205], v[16:19]
	v_mfma_f32_16x16x32_bf16 v[4:7], v[148:151], v[210:213], v[4:7]
	v_mfma_f32_16x16x32_bf16 v[0:3], v[156:159], v[210:213], v[0:3]
	s_barrier
	s_add_i32 s53, s53, 2
	s_add_u32 s26, s26, 0x100
	s_addc_u32 s27, s27, 0
	s_add_u32 s51, s51, 0x100
	s_addc_u32 s52, s52, 0
	s_cmp_gt_u32 s53, 13
	s_cbranch_scc0 .LBB0_380
	s_and_b64 vcc, exec, s[12:13]
	s_cbranch_vccz .LBB0_383
	s_barrier

.LBB0_471:
	v_add_u32_e32 v158, s46, v166
	v_add_u32_e32 v182, s47, v166
	ds_read_b128 v[112:115], v158
	ds_read_b128 v[120:123], v158 offset:1024
	ds_read_b128 v[154:157], v158 offset:2048
	ds_read_b128 v[158:161], v158 offset:3072
	ds_read_b128 v[170:173], v182
	ds_read_b128 v[174:177], v182 offset:1024
	ds_read_b128 v[178:181], v182 offset:2048
	ds_read_b128 v[186:189], v182 offset:3072
	s_add_u32 s2, s22, 0xfffc0080
	s_addc_u32 s26, s23, -1
	s_and_b64 s[24:25], s[24:25], exec
	s_cselect_b32 s27, s15, s26
	s_cselect_b32 s26, s52, s2
	s_cselect_b32 s25, s13, s59
	s_cselect_b32 s24, s53, s58
	v_lshl_add_u64 v[182:183], s[22:23], 0, v[146:147]
	s_add_i32 m0, s36, 0xc000
	ds_read_b128 v[192:195], v168
	ds_read_b128 v[196:199], v168 offset:1024
	ds_read_b128 v[200:203], v168 offset:2048
	ds_read_b128 v[204:207], v168 offset:3072
	ds_read_b128 v[208:211], v168 offset:4096
	ds_read_b128 v[212:215], v168 offset:5120
	ds_read_b128 v[216:219], v168 offset:6144
	ds_read_b128 v[220:223], v168 offset:7168
	global_load_lds_dwordx4 v[182:183], off
	v_lshl_add_u64 v[182:183], s[22:23], 0, v[148:149]
	s_add_i32 m0, s36, 0xe000
	s_nop 0
	global_load_lds_dwordx4 v[182:183], off
	s_waitcnt vmcnt(8)
	s_waitcnt lgkmcnt(0)
	s_barrier
	s_waitcnt lgkmcnt(0)
	v_mfma_f32_16x16x32_bf16 v[132:135], v[112:115], v[192:195], v[132:135]
	v_mfma_f32_16x16x32_bf16 v[124:127], v[154:157], v[192:195], v[124:127]
	v_mfma_f32_16x16x32_bf16 v[108:111], v[112:115], v[200:203], v[108:111]
	v_mfma_f32_16x16x32_bf16 v[100:103], v[154:157], v[200:203], v[100:103]
	v_mfma_f32_16x16x32_bf16 v[92:95], v[112:115], v[208:211], v[92:95]
	v_mfma_f32_16x16x32_bf16 v[84:87], v[154:157], v[208:211], v[84:87]
	v_mfma_f32_16x16x32_bf16 v[76:79], v[112:115], v[216:219], v[76:79]
	v_mfma_f32_16x16x32_bf16 v[68:71], v[154:157], v[216:219], v[68:71]
	v_mfma_f32_16x16x32_bf16 v[132:135], v[120:123], v[196:199], v[132:135]
	v_mfma_f32_16x16x32_bf16 v[124:127], v[158:161], v[196:199], v[124:127]
	v_mfma_f32_16x16x32_bf16 v[108:111], v[120:123], v[204:207], v[108:111]
	v_mfma_f32_16x16x32_bf16 v[100:103], v[158:161], v[204:207], v[100:103]
	v_mfma_f32_16x16x32_bf16 v[92:95], v[120:123], v[212:215], v[92:95]
	v_mfma_f32_16x16x32_bf16 v[84:87], v[158:161], v[212:215], v[84:87]
	v_mfma_f32_16x16x32_bf16 v[76:79], v[120:123], v[220:223], v[76:79]
	v_mfma_f32_16x16x32_bf16 v[68:71], v[158:161], v[220:223], v[68:71]
	v_mfma_f32_16x16x32_bf16 v[128:131], v[170:173], v[192:195], v[128:131]
	v_mfma_f32_16x16x32_bf16 v[116:119], v[178:181], v[192:195], v[116:119]
	v_mfma_f32_16x16x32_bf16 v[104:107], v[170:173], v[200:203], v[104:107]
	v_mfma_f32_16x16x32_bf16 v[96:99], v[178:181], v[200:203], v[96:99]
	v_mfma_f32_16x16x32_bf16 v[88:91], v[170:173], v[208:211], v[88:91]
	v_mfma_f32_16x16x32_bf16 v[80:83], v[178:181], v[208:211], v[80:83]
	v_mfma_f32_16x16x32_bf16 v[72:75], v[170:173], v[216:219], v[72:75]
	v_mfma_f32_16x16x32_bf16 v[64:67], v[178:181], v[216:219], v[64:67]
	v_mfma_f32_16x16x32_bf16 v[128:131], v[174:177], v[196:199], v[128:131]
	v_mfma_f32_16x16x32_bf16 v[116:119], v[186:189], v[196:199], v[116:119]
	v_mfma_f32_16x16x32_bf16 v[104:107], v[174:177], v[204:207], v[104:107]
	v_mfma_f32_16x16x32_bf16 v[96:99], v[186:189], v[204:207], v[96:99]
	v_mfma_f32_16x16x32_bf16 v[88:91], v[174:177], v[212:215], v[88:91]
	v_mfma_f32_16x16x32_bf16 v[80:83], v[186:189], v[212:215], v[80:83]
	v_mfma_f32_16x16x32_bf16 v[72:75], v[174:177], v[220:223], v[72:75]
	v_mfma_f32_16x16x32_bf16 v[64:67], v[186:189], v[220:223], v[64:67]
	s_barrier
	s_add_i32 s2, s46, s21
	v_lshl_add_u64 v[182:183], s[24:25], 0, v[138:139]
	s_mov_b32 m0, s2
	ds_read_b128 v[192:195], v168 offset:16384
	ds_read_b128 v[196:199], v168 offset:17408
	ds_read_b128 v[200:203], v168 offset:18432
	ds_read_b128 v[204:207], v168 offset:19456
	ds_read_b128 v[208:211], v168 offset:20480
	ds_read_b128 v[212:215], v168 offset:21504
	ds_read_b128 v[216:219], v168 offset:22528
	ds_read_b128 v[220:223], v168 offset:23552
	global_load_lds_dwordx4 v[182:183], off
	s_add_i32 m0, s2, 0x2000
	s_add_u32 s62, s24, 0x40000
	v_lshl_add_u64 v[224:225], s[24:25], 0, v[142:143]
	s_addc_u32 s63, s25, 0
	s_add_i32 s2, s47, s21
	global_load_lds_dwordx4 v[224:225], off
	v_lshl_add_u64 v[226:227], s[62:63], 0, v[138:139]
	s_mov_b32 m0, s2
	v_lshl_add_u64 v[228:229], s[26:27], 0, v[140:141]
	global_load_lds_dwordx4 v[226:227], off
	v_lshl_add_u64 v[226:227], s[62:63], 0, v[142:143]
	s_add_i32 m0, s2, 0x2000
	s_nop 0
	global_load_lds_dwordx4 v[226:227], off
	v_lshl_add_u64 v[226:227], s[26:27], 0, v[136:137]
	s_mov_b32 m0, s36
	s_nop 0
	global_load_lds_dwordx4 v[226:227], off
	s_mov_b32 m0, s37
	s_nop 0
	global_load_lds_dwordx4 v[228:229], off
	s_waitcnt vmcnt(8)
	s_waitcnt lgkmcnt(0)
	s_barrier
	s_waitcnt lgkmcnt(0)
	v_mfma_f32_16x16x32_bf16 v[60:63], v[112:115], v[192:195], v[60:63]
	v_mfma_f32_16x16x32_bf16 v[52:55], v[154:157], v[192:195], v[52:55]
	v_mfma_f32_16x16x32_bf16 v[44:47], v[112:115], v[200:203], v[44:47]
	v_mfma_f32_16x16x32_bf16 v[36:39], v[154:157], v[200:203], v[36:39]
	v_mfma_f32_16x16x32_bf16 v[28:31], v[112:115], v[208:211], v[28:31]
	v_mfma_f32_16x16x32_bf16 v[20:23], v[154:157], v[208:211], v[20:23]
	v_mfma_f32_16x16x32_bf16 v[12:15], v[112:115], v[216:219], v[12:15]
	v_mfma_f32_16x16x32_bf16 v[4:7], v[154:157], v[216:219], v[4:7]
	v_mfma_f32_16x16x32_bf16 v[60:63], v[120:123], v[196:199], v[60:63]
	v_mfma_f32_16x16x32_bf16 v[52:55], v[158:161], v[196:199], v[52:55]
	v_mfma_f32_16x16x32_bf16 v[44:47], v[120:123], v[204:207], v[44:47]
	v_mfma_f32_16x16x32_bf16 v[36:39], v[158:161], v[204:207], v[36:39]
	v_mfma_f32_16x16x32_bf16 v[28:31], v[120:123], v[212:215], v[28:31]
	v_mfma_f32_16x16x32_bf16 v[20:23], v[158:161], v[212:215], v[20:23]
	v_mfma_f32_16x16x32_bf16 v[12:15], v[120:123], v[220:223], v[12:15]
	v_mfma_f32_16x16x32_bf16 v[4:7], v[158:161], v[220:223], v[4:7]
	v_mfma_f32_16x16x32_bf16 v[56:59], v[170:173], v[192:195], v[56:59]
	v_mfma_f32_16x16x32_bf16 v[48:51], v[178:181], v[192:195], v[48:51]
	v_mfma_f32_16x16x32_bf16 v[40:43], v[170:173], v[200:203], v[40:43]
	v_mfma_f32_16x16x32_bf16 v[32:35], v[178:181], v[200:203], v[32:35]
	v_mfma_f32_16x16x32_bf16 v[24:27], v[170:173], v[208:211], v[24:27]
	v_mfma_f32_16x16x32_bf16 v[16:19], v[178:181], v[208:211], v[16:19]
	v_mfma_f32_16x16x32_bf16 v[8:11], v[170:173], v[216:219], v[8:11]
	v_mfma_f32_16x16x32_bf16 v[0:3], v[178:181], v[216:219], v[0:3]
	v_mfma_f32_16x16x32_bf16 v[56:59], v[174:177], v[196:199], v[56:59]
	v_mfma_f32_16x16x32_bf16 v[48:51], v[186:189], v[196:199], v[48:51]
	v_mfma_f32_16x16x32_bf16 v[40:43], v[174:177], v[204:207], v[40:43]
	v_mfma_f32_16x16x32_bf16 v[32:35], v[186:189], v[204:207], v[32:35]
	v_mfma_f32_16x16x32_bf16 v[24:27], v[174:177], v[212:215], v[24:27]
	v_mfma_f32_16x16x32_bf16 v[16:19], v[186:189], v[212:215], v[16:19]
	v_mfma_f32_16x16x32_bf16 v[8:11], v[174:177], v[220:223], v[8:11]
	v_mfma_f32_16x16x32_bf16 v[0:3], v[186:189], v[220:223], v[0:3]
	s_barrier
	s_add_i32 s2, 0, 0x18000
	s_add_i32 s61, 0, 0x1c000
	v_add_u32_e32 v158, s2, v166
	v_add_u32_e32 v185, s61, v166
	ds_read_b128 v[112:115], v158
	ds_read_b128 v[120:123], v158 offset:1024
	ds_read_b128 v[154:157], v158 offset:2048
	ds_read_b128 v[158:161], v158 offset:3072
	ds_read_b128 v[170:173], v185
	ds_read_b128 v[174:177], v185 offset:1024
	ds_read_b128 v[178:181], v185 offset:2048
	ds_read_b128 v[186:189], v185 offset:3072
	s_add_u32 s26, s26, 0x40000
	s_addc_u32 s27, s27, 0
	s_mov_b32 m0, s38
	v_lshl_add_u64 v[230:231], s[26:27], 0, v[136:137]
	ds_read_b128 v[192:195], v168 offset:32768
	ds_read_b128 v[196:199], v168 offset:33792
	ds_read_b128 v[200:203], v168 offset:34816
	ds_read_b128 v[204:207], v168 offset:35840
	ds_read_b128 v[208:211], v168 offset:36864
	ds_read_b128 v[212:215], v168 offset:37888
	ds_read_b128 v[216:219], v168 offset:38912
	ds_read_b128 v[220:223], v168 offset:39936
	global_load_lds_dwordx4 v[230:231], off
	v_lshl_add_u64 v[230:231], s[26:27], 0, v[140:141]
	s_mov_b32 m0, s39
	s_nop 0
	global_load_lds_dwordx4 v[230:231], off
	s_waitcnt vmcnt(8)
	s_waitcnt lgkmcnt(0)
	s_barrier
	s_waitcnt lgkmcnt(0)
	v_mfma_f32_16x16x32_bf16 v[132:135], v[112:115], v[192:195], v[132:135]
	v_mfma_f32_16x16x32_bf16 v[124:127], v[154:157], v[192:195], v[124:127]
	v_mfma_f32_16x16x32_bf16 v[108:111], v[112:115], v[200:203], v[108:111]
	v_mfma_f32_16x16x32_bf16 v[100:103], v[154:157], v[200:203], v[100:103]
	v_mfma_f32_16x16x32_bf16 v[92:95], v[112:115], v[208:211], v[92:95]
	v_mfma_f32_16x16x32_bf16 v[84:87], v[154:157], v[208:211], v[84:87]
	v_mfma_f32_16x16x32_bf16 v[76:79], v[112:115], v[216:219], v[76:79]
	v_mfma_f32_16x16x32_bf16 v[68:71], v[154:157], v[216:219], v[68:71]
	v_mfma_f32_16x16x32_bf16 v[132:135], v[120:123], v[196:199], v[132:135]
	v_mfma_f32_16x16x32_bf16 v[124:127], v[158:161], v[196:199], v[124:127]
	v_mfma_f32_16x16x32_bf16 v[108:111], v[120:123], v[204:207], v[108:111]
	v_mfma_f32_16x16x32_bf16 v[100:103], v[158:161], v[204:207], v[100:103]
	v_mfma_f32_16x16x32_bf16 v[92:95], v[120:123], v[212:215], v[92:95]
	v_mfma_f32_16x16x32_bf16 v[84:87], v[158:161], v[212:215], v[84:87]
	v_mfma_f32_16x16x32_bf16 v[76:79], v[120:123], v[220:223], v[76:79]
	v_mfma_f32_16x16x32_bf16 v[68:71], v[158:161], v[220:223], v[68:71]
	v_mfma_f32_16x16x32_bf16 v[128:131], v[170:173], v[192:195], v[128:131]
	v_mfma_f32_16x16x32_bf16 v[116:119], v[178:181], v[192:195], v[116:119]
	v_mfma_f32_16x16x32_bf16 v[104:107], v[170:173], v[200:203], v[104:107]
	v_mfma_f32_16x16x32_bf16 v[96:99], v[178:181], v[200:203], v[96:99]
	v_mfma_f32_16x16x32_bf16 v[88:91], v[170:173], v[208:211], v[88:91]
	v_mfma_f32_16x16x32_bf16 v[80:83], v[178:181], v[208:211], v[80:83]
	v_mfma_f32_16x16x32_bf16 v[72:75], v[170:173], v[216:219], v[72:75]
	v_mfma_f32_16x16x32_bf16 v[64:67], v[178:181], v[216:219], v[64:67]
	v_mfma_f32_16x16x32_bf16 v[128:131], v[174:177], v[196:199], v[128:131]
	v_mfma_f32_16x16x32_bf16 v[116:119], v[186:189], v[196:199], v[116:119]
	v_mfma_f32_16x16x32_bf16 v[104:107], v[174:177], v[204:207], v[104:107]
	v_mfma_f32_16x16x32_bf16 v[96:99], v[186:189], v[204:207], v[96:99]
	v_mfma_f32_16x16x32_bf16 v[88:91], v[174:177], v[212:215], v[88:91]
	v_mfma_f32_16x16x32_bf16 v[80:83], v[186:189], v[212:215], v[80:83]
	v_mfma_f32_16x16x32_bf16 v[72:75], v[174:177], v[220:223], v[72:75]
	v_mfma_f32_16x16x32_bf16 v[64:67], v[186:189], v[220:223], v[64:67]
	s_barrier
	s_add_i32 s2, s2, s21
	v_lshl_add_u64 v[182:183], v[182:183], 0, s[8:9]
	s_mov_b32 m0, s2
	ds_read_b128 v[192:195], v168 offset:49152
	ds_read_b128 v[196:199], v168 offset:50176
	ds_read_b128 v[200:203], v168 offset:51200
	ds_read_b128 v[204:207], v168 offset:52224
	ds_read_b128 v[208:211], v168 offset:53248
	ds_read_b128 v[212:215], v168 offset:54272
	ds_read_b128 v[216:219], v168 offset:55296
	ds_read_b128 v[220:223], v168 offset:56320
	global_load_lds_dwordx4 v[182:183], off
	s_add_i32 m0, s2, 0x2000
	s_add_u32 s24, s24, 0x40080
	v_lshl_add_u64 v[182:183], v[224:225], 0, s[8:9]
	s_addc_u32 s25, s25, 0
	s_add_i32 s2, s61, s21
	global_load_lds_dwordx4 v[182:183], off
	v_lshl_add_u64 v[182:183], s[24:25], 0, v[138:139]
	s_mov_b32 m0, s2
	s_nop 0
	global_load_lds_dwordx4 v[182:183], off
	v_lshl_add_u64 v[182:183], s[24:25], 0, v[142:143]
	s_add_i32 m0, s2, 0x2000
	s_nop 0
	global_load_lds_dwordx4 v[182:183], off
	v_lshl_add_u64 v[182:183], v[226:227], 0, s[8:9]
	s_mov_b32 m0, s43
	s_nop 0
	global_load_lds_dwordx4 v[182:183], off
	v_lshl_add_u64 v[182:183], v[228:229], 0, s[8:9]
	s_mov_b32 m0, s44
	s_nop 0
	global_load_lds_dwordx4 v[182:183], off
	s_waitcnt vmcnt(8)
	s_waitcnt lgkmcnt(0)
	s_barrier
	s_waitcnt lgkmcnt(0)
	v_mfma_f32_16x16x32_bf16 v[60:63], v[112:115], v[192:195], v[60:63]
	v_mfma_f32_16x16x32_bf16 v[52:55], v[154:157], v[192:195], v[52:55]
	v_mfma_f32_16x16x32_bf16 v[44:47], v[112:115], v[200:203], v[44:47]
	v_mfma_f32_16x16x32_bf16 v[36:39], v[154:157], v[200:203], v[36:39]
	v_mfma_f32_16x16x32_bf16 v[28:31], v[112:115], v[208:211], v[28:31]
	v_mfma_f32_16x16x32_bf16 v[20:23], v[154:157], v[208:211], v[20:23]
	v_mfma_f32_16x16x32_bf16 v[12:15], v[112:115], v[216:219], v[12:15]
	v_mfma_f32_16x16x32_bf16 v[4:7], v[154:157], v[216:219], v[4:7]
	v_mfma_f32_16x16x32_bf16 v[60:63], v[120:123], v[196:199], v[60:63]
	v_mfma_f32_16x16x32_bf16 v[52:55], v[158:161], v[196:199], v[52:55]
	v_mfma_f32_16x16x32_bf16 v[44:47], v[120:123], v[204:207], v[44:47]
	v_mfma_f32_16x16x32_bf16 v[36:39], v[158:161], v[204:207], v[36:39]
	v_mfma_f32_16x16x32_bf16 v[28:31], v[120:123], v[212:215], v[28:31]
	v_mfma_f32_16x16x32_bf16 v[20:23], v[158:161], v[212:215], v[20:23]
	v_mfma_f32_16x16x32_bf16 v[12:15], v[120:123], v[220:223], v[12:15]
	v_mfma_f32_16x16x32_bf16 v[4:7], v[158:161], v[220:223], v[4:7]
	v_mfma_f32_16x16x32_bf16 v[56:59], v[170:173], v[192:195], v[56:59]
	v_mfma_f32_16x16x32_bf16 v[48:51], v[178:181], v[192:195], v[48:51]
	v_mfma_f32_16x16x32_bf16 v[40:43], v[170:173], v[200:203], v[40:43]
	v_mfma_f32_16x16x32_bf16 v[32:35], v[178:181], v[200:203], v[32:35]
	v_mfma_f32_16x16x32_bf16 v[24:27], v[170:173], v[208:211], v[24:27]
	v_mfma_f32_16x16x32_bf16 v[16:19], v[178:181], v[208:211], v[16:19]
	v_mfma_f32_16x16x32_bf16 v[8:11], v[170:173], v[216:219], v[8:11]
	v_mfma_f32_16x16x32_bf16 v[0:3], v[178:181], v[216:219], v[0:3]
	v_mfma_f32_16x16x32_bf16 v[56:59], v[174:177], v[196:199], v[56:59]
	v_mfma_f32_16x16x32_bf16 v[48:51], v[186:189], v[196:199], v[48:51]
	v_mfma_f32_16x16x32_bf16 v[40:43], v[174:177], v[204:207], v[40:43]
	v_mfma_f32_16x16x32_bf16 v[32:35], v[186:189], v[204:207], v[32:35]
	v_mfma_f32_16x16x32_bf16 v[24:27], v[174:177], v[212:215], v[24:27]
	v_mfma_f32_16x16x32_bf16 v[16:19], v[186:189], v[212:215], v[16:19]
	v_mfma_f32_16x16x32_bf16 v[8:11], v[174:177], v[220:223], v[8:11]
	v_mfma_f32_16x16x32_bf16 v[0:3], v[186:189], v[220:223], v[0:3]
	s_barrier
	s_add_i32 s60, s60, 2
	s_add_u32 s22, s22, 0x100
	s_addc_u32 s23, s23, 0
	s_add_u32 s58, s58, 0x100
	s_addc_u32 s59, s59, 0
	s_cmp_gt_u32 s60, 13
	s_cbranch_scc1 .LBB0_474

.LBB0_588:
	ds_read_b128 v[128:131], v179
	ds_read_b128 v[132:135], v179 offset:1024
	ds_read_b128 v[136:139], v179 offset:2048
	ds_read_b128 v[140:143], v179 offset:3072
	ds_read_b128 v[144:147], v180
	ds_read_b128 v[148:151], v180 offset:1024
	ds_read_b128 v[164:167], v180 offset:2048
	ds_read_b128 v[168:171], v180 offset:3072
	s_add_u32 s16, s14, 0xfff50080
	s_addc_u32 s17, s15, -1
	s_cmp_eq_u32 s43, 40
	s_cselect_b32 s19, s1, s17
	s_cselect_b32 s18, s0, s16
	s_cselect_b32 s17, s13, s42
	s_cselect_b32 s16, s12, s41
	v_lshl_add_u64 v[172:173], s[14:15], 0, v[156:157]
	s_add_i32 m0, s24, 0xc000
	ds_read_b128 v[186:189], v181
	ds_read_b128 v[192:195], v181 offset:1024
	ds_read_b128 v[196:199], v181 offset:2048
	ds_read_b128 v[200:203], v181 offset:3072
	ds_read_b128 v[204:207], v181 offset:4096
	ds_read_b128 v[208:211], v181 offset:5120
	ds_read_b128 v[212:215], v181 offset:6144
	ds_read_b128 v[216:219], v181 offset:7168
	global_load_lds_dwordx4 v[172:173], off
	v_lshl_add_u64 v[172:173], s[14:15], 0, v[158:159]
	s_add_i32 m0, s24, 0xe000
	s_nop 0
	global_load_lds_dwordx4 v[172:173], off
	s_waitcnt vmcnt(8)
	s_waitcnt lgkmcnt(0)
	s_barrier
	s_waitcnt lgkmcnt(0)
	v_mfma_f32_16x16x32_bf16 v[124:127], v[128:131], v[186:189], v[124:127]
	v_mfma_f32_16x16x32_bf16 v[120:123], v[136:139], v[186:189], v[120:123]
	v_mfma_f32_16x16x32_bf16 v[116:119], v[128:131], v[196:199], v[116:119]
	v_mfma_f32_16x16x32_bf16 v[112:115], v[136:139], v[196:199], v[112:115]
	v_mfma_f32_16x16x32_bf16 v[100:103], v[128:131], v[204:207], v[100:103]
	v_mfma_f32_16x16x32_bf16 v[88:91], v[136:139], v[204:207], v[88:91]
	v_mfma_f32_16x16x32_bf16 v[84:87], v[128:131], v[212:215], v[84:87]
	v_mfma_f32_16x16x32_bf16 v[76:79], v[136:139], v[212:215], v[76:79]
	v_mfma_f32_16x16x32_bf16 v[124:127], v[132:135], v[192:195], v[124:127]
	v_mfma_f32_16x16x32_bf16 v[120:123], v[140:143], v[192:195], v[120:123]
	v_mfma_f32_16x16x32_bf16 v[116:119], v[132:135], v[200:203], v[116:119]
	v_mfma_f32_16x16x32_bf16 v[112:115], v[140:143], v[200:203], v[112:115]
	v_mfma_f32_16x16x32_bf16 v[100:103], v[132:135], v[208:211], v[100:103]
	v_mfma_f32_16x16x32_bf16 v[88:91], v[140:143], v[208:211], v[88:91]
	v_mfma_f32_16x16x32_bf16 v[84:87], v[132:135], v[216:219], v[84:87]
	v_mfma_f32_16x16x32_bf16 v[76:79], v[140:143], v[216:219], v[76:79]
	v_mfma_f32_16x16x32_bf16 v[108:111], v[144:147], v[186:189], v[108:111]
	v_mfma_f32_16x16x32_bf16 v[104:107], v[164:167], v[186:189], v[104:107]
	v_mfma_f32_16x16x32_bf16 v[96:99], v[144:147], v[196:199], v[96:99]
	v_mfma_f32_16x16x32_bf16 v[92:95], v[164:167], v[196:199], v[92:95]
	v_mfma_f32_16x16x32_bf16 v[80:83], v[144:147], v[204:207], v[80:83]
	v_mfma_f32_16x16x32_bf16 v[72:75], v[164:167], v[204:207], v[72:75]
	v_mfma_f32_16x16x32_bf16 v[68:71], v[144:147], v[212:215], v[68:71]
	v_mfma_f32_16x16x32_bf16 v[64:67], v[164:167], v[212:215], v[64:67]
	v_mfma_f32_16x16x32_bf16 v[108:111], v[148:151], v[192:195], v[108:111]
	v_mfma_f32_16x16x32_bf16 v[104:107], v[168:171], v[192:195], v[104:107]
	v_mfma_f32_16x16x32_bf16 v[96:99], v[148:151], v[200:203], v[96:99]
	v_mfma_f32_16x16x32_bf16 v[92:95], v[168:171], v[200:203], v[92:95]
	v_mfma_f32_16x16x32_bf16 v[80:83], v[148:151], v[208:211], v[80:83]
	v_mfma_f32_16x16x32_bf16 v[72:75], v[168:171], v[208:211], v[72:75]
	v_mfma_f32_16x16x32_bf16 v[68:71], v[148:151], v[216:219], v[68:71]
	v_mfma_f32_16x16x32_bf16 v[64:67], v[168:171], v[216:219], v[64:67]
	s_barrier
	s_add_i32 s44, s35, s22
	v_lshl_add_u64 v[172:173], s[16:17], 0, v[152:153]
	s_mov_b32 m0, s44
	ds_read_b128 v[186:189], v181 offset:16384
	ds_read_b128 v[192:195], v181 offset:17408
	ds_read_b128 v[196:199], v181 offset:18432
	ds_read_b128 v[200:203], v181 offset:19456
	ds_read_b128 v[204:207], v181 offset:20480
	ds_read_b128 v[208:211], v181 offset:21504
	ds_read_b128 v[212:215], v181 offset:22528
	ds_read_b128 v[216:219], v181 offset:23552
	global_load_lds_dwordx4 v[172:173], off
	s_add_i32 m0, s44, 0x2000
	s_add_u32 s44, s16, 0xb0000
	v_lshl_add_u64 v[182:183], s[16:17], 0, v[154:155]
	s_addc_u32 s45, s17, 0
	s_add_i32 s46, s36, s22
	global_load_lds_dwordx4 v[182:183], off
	v_lshl_add_u64 v[220:221], s[44:45], 0, v[152:153]
	s_mov_b32 m0, s46
	v_lshl_add_u64 v[222:223], s[18:19], 0, v[154:155]
	global_load_lds_dwordx4 v[220:221], off
	v_lshl_add_u64 v[220:221], s[44:45], 0, v[154:155]
	s_add_i32 m0, s46, 0x2000
	s_nop 0
	global_load_lds_dwordx4 v[220:221], off
	v_lshl_add_u64 v[220:221], s[18:19], 0, v[152:153]
	s_mov_b32 m0, s24
	s_nop 0
	global_load_lds_dwordx4 v[220:221], off
	s_mov_b32 m0, s25
	s_nop 0
	global_load_lds_dwordx4 v[222:223], off
	s_waitcnt vmcnt(8)
	s_waitcnt lgkmcnt(0)
	s_barrier
	s_waitcnt lgkmcnt(0)
	v_mfma_f32_16x16x32_bf16 v[60:63], v[128:131], v[186:189], v[60:63]
	v_mfma_f32_16x16x32_bf16 v[56:59], v[136:139], v[186:189], v[56:59]
	v_mfma_f32_16x16x32_bf16 v[52:55], v[128:131], v[196:199], v[52:55]
	v_mfma_f32_16x16x32_bf16 v[48:51], v[136:139], v[196:199], v[48:51]
	v_mfma_f32_16x16x32_bf16 v[40:43], v[128:131], v[204:207], v[40:43]
	v_mfma_f32_16x16x32_bf16 v[28:31], v[136:139], v[204:207], v[28:31]
	v_mfma_f32_16x16x32_bf16 v[16:19], v[128:131], v[212:215], v[16:19]
	v_mfma_f32_16x16x32_bf16 v[8:11], v[136:139], v[212:215], v[8:11]
	v_mfma_f32_16x16x32_bf16 v[60:63], v[132:135], v[192:195], v[60:63]
	v_mfma_f32_16x16x32_bf16 v[56:59], v[140:143], v[192:195], v[56:59]
	v_mfma_f32_16x16x32_bf16 v[52:55], v[132:135], v[200:203], v[52:55]
	v_mfma_f32_16x16x32_bf16 v[48:51], v[140:143], v[200:203], v[48:51]
	v_mfma_f32_16x16x32_bf16 v[40:43], v[132:135], v[208:211], v[40:43]
	v_mfma_f32_16x16x32_bf16 v[28:31], v[140:143], v[208:211], v[28:31]
	v_mfma_f32_16x16x32_bf16 v[16:19], v[132:135], v[216:219], v[16:19]
	v_mfma_f32_16x16x32_bf16 v[8:11], v[140:143], v[216:219], v[8:11]
	v_mfma_f32_16x16x32_bf16 v[44:47], v[144:147], v[186:189], v[44:47]
	v_mfma_f32_16x16x32_bf16 v[36:39], v[164:167], v[186:189], v[36:39]
	v_mfma_f32_16x16x32_bf16 v[32:35], v[144:147], v[196:199], v[32:35]
	v_mfma_f32_16x16x32_bf16 v[24:27], v[164:167], v[196:199], v[24:27]
	v_mfma_f32_16x16x32_bf16 v[20:23], v[144:147], v[204:207], v[20:23]
	v_mfma_f32_16x16x32_bf16 v[12:15], v[164:167], v[204:207], v[12:15]
	v_mfma_f32_16x16x32_bf16 v[4:7], v[144:147], v[212:215], v[4:7]
	v_mfma_f32_16x16x32_bf16 v[0:3], v[164:167], v[212:215], v[0:3]
	v_mfma_f32_16x16x32_bf16 v[44:47], v[148:151], v[192:195], v[44:47]
	v_mfma_f32_16x16x32_bf16 v[36:39], v[168:171], v[192:195], v[36:39]
	v_mfma_f32_16x16x32_bf16 v[32:35], v[148:151], v[200:203], v[32:35]
	v_mfma_f32_16x16x32_bf16 v[24:27], v[168:171], v[200:203], v[24:27]
	v_mfma_f32_16x16x32_bf16 v[20:23], v[148:151], v[208:211], v[20:23]
	v_mfma_f32_16x16x32_bf16 v[12:15], v[168:171], v[208:211], v[12:15]
	v_mfma_f32_16x16x32_bf16 v[4:7], v[148:151], v[216:219], v[4:7]
	v_mfma_f32_16x16x32_bf16 v[0:3], v[168:171], v[216:219], v[0:3]
	s_barrier
	s_add_i32 s44, 0, 0x18000
	s_add_i32 s45, 0, 0x1c000
	v_add_u32_e32 v140, s44, v175
	v_add_u32_e32 v168, s45, v175
	ds_read_b128 v[128:131], v140
	ds_read_b128 v[132:135], v140 offset:1024
	ds_read_b128 v[136:139], v140 offset:2048
	ds_read_b128 v[140:143], v140 offset:3072
	ds_read_b128 v[144:147], v168
	ds_read_b128 v[148:151], v168 offset:1024
	ds_read_b128 v[164:167], v168 offset:2048
	ds_read_b128 v[168:171], v168 offset:3072
	s_add_u32 s18, s18, 0xb0000
	s_addc_u32 s19, s19, 0
	s_mov_b32 m0, s26
	v_lshl_add_u64 v[224:225], s[18:19], 0, v[152:153]
	ds_read_b128 v[186:189], v181 offset:32768
	ds_read_b128 v[192:195], v181 offset:33792
	ds_read_b128 v[196:199], v181 offset:34816
	ds_read_b128 v[200:203], v181 offset:35840
	ds_read_b128 v[204:207], v181 offset:36864
	ds_read_b128 v[208:211], v181 offset:37888
	ds_read_b128 v[212:215], v181 offset:38912
	ds_read_b128 v[216:219], v181 offset:39936
	global_load_lds_dwordx4 v[224:225], off
	v_lshl_add_u64 v[224:225], s[18:19], 0, v[154:155]
	s_mov_b32 m0, s27
	s_nop 0
	global_load_lds_dwordx4 v[224:225], off
	s_waitcnt vmcnt(8)
	s_waitcnt lgkmcnt(0)
	s_barrier
	s_waitcnt lgkmcnt(0)
	v_mfma_f32_16x16x32_bf16 v[124:127], v[128:131], v[186:189], v[124:127]
	v_mfma_f32_16x16x32_bf16 v[120:123], v[136:139], v[186:189], v[120:123]
	v_mfma_f32_16x16x32_bf16 v[116:119], v[128:131], v[196:199], v[116:119]
	v_mfma_f32_16x16x32_bf16 v[112:115], v[136:139], v[196:199], v[112:115]
	v_mfma_f32_16x16x32_bf16 v[100:103], v[128:131], v[204:207], v[100:103]
	v_mfma_f32_16x16x32_bf16 v[88:91], v[136:139], v[204:207], v[88:91]
	v_mfma_f32_16x16x32_bf16 v[84:87], v[128:131], v[212:215], v[84:87]
	v_mfma_f32_16x16x32_bf16 v[76:79], v[136:139], v[212:215], v[76:79]
	v_mfma_f32_16x16x32_bf16 v[124:127], v[132:135], v[192:195], v[124:127]
	v_mfma_f32_16x16x32_bf16 v[120:123], v[140:143], v[192:195], v[120:123]
	v_mfma_f32_16x16x32_bf16 v[116:119], v[132:135], v[200:203], v[116:119]
	v_mfma_f32_16x16x32_bf16 v[112:115], v[140:143], v[200:203], v[112:115]
	v_mfma_f32_16x16x32_bf16 v[100:103], v[132:135], v[208:211], v[100:103]
	v_mfma_f32_16x16x32_bf16 v[88:91], v[140:143], v[208:211], v[88:91]
	v_mfma_f32_16x16x32_bf16 v[84:87], v[132:135], v[216:219], v[84:87]
	v_mfma_f32_16x16x32_bf16 v[76:79], v[140:143], v[216:219], v[76:79]
	v_mfma_f32_16x16x32_bf16 v[108:111], v[144:147], v[186:189], v[108:111]
	v_mfma_f32_16x16x32_bf16 v[104:107], v[164:167], v[186:189], v[104:107]
	v_mfma_f32_16x16x32_bf16 v[96:99], v[144:147], v[196:199], v[96:99]
	v_mfma_f32_16x16x32_bf16 v[92:95], v[164:167], v[196:199], v[92:95]
	v_mfma_f32_16x16x32_bf16 v[80:83], v[144:147], v[204:207], v[80:83]
	v_mfma_f32_16x16x32_bf16 v[72:75], v[164:167], v[204:207], v[72:75]
	v_mfma_f32_16x16x32_bf16 v[68:71], v[144:147], v[212:215], v[68:71]
	v_mfma_f32_16x16x32_bf16 v[64:67], v[164:167], v[212:215], v[64:67]
	v_mfma_f32_16x16x32_bf16 v[108:111], v[148:151], v[192:195], v[108:111]
	v_mfma_f32_16x16x32_bf16 v[104:107], v[168:171], v[192:195], v[104:107]
	v_mfma_f32_16x16x32_bf16 v[96:99], v[148:151], v[200:203], v[96:99]
	v_mfma_f32_16x16x32_bf16 v[92:95], v[168:171], v[200:203], v[92:95]
	v_mfma_f32_16x16x32_bf16 v[80:83], v[148:151], v[208:211], v[80:83]
	v_mfma_f32_16x16x32_bf16 v[72:75], v[168:171], v[208:211], v[72:75]
	v_mfma_f32_16x16x32_bf16 v[68:71], v[148:151], v[216:219], v[68:71]
	v_mfma_f32_16x16x32_bf16 v[64:67], v[168:171], v[216:219], v[64:67]
	s_barrier
	s_add_i32 s18, s44, s22
	v_lshl_add_u64 v[172:173], v[172:173], 0, s[8:9]
	s_mov_b32 m0, s18
	ds_read_b128 v[186:189], v181 offset:49152
	ds_read_b128 v[192:195], v181 offset:50176
	ds_read_b128 v[196:199], v181 offset:51200
	ds_read_b128 v[200:203], v181 offset:52224
	ds_read_b128 v[204:207], v181 offset:53248
	ds_read_b128 v[208:211], v181 offset:54272
	ds_read_b128 v[212:215], v181 offset:55296
	ds_read_b128 v[216:219], v181 offset:56320
	global_load_lds_dwordx4 v[172:173], off
	s_add_i32 m0, s18, 0x2000
	s_add_u32 s16, s16, 0xb0080
	v_lshl_add_u64 v[172:173], v[182:183], 0, s[8:9]
	s_addc_u32 s17, s17, 0
	s_add_i32 s18, s45, s22
	global_load_lds_dwordx4 v[172:173], off
	v_lshl_add_u64 v[172:173], s[16:17], 0, v[152:153]
	s_mov_b32 m0, s18
	s_nop 0
	global_load_lds_dwordx4 v[172:173], off
	v_lshl_add_u64 v[172:173], s[16:17], 0, v[154:155]
	s_add_i32 m0, s18, 0x2000
	s_nop 0
	global_load_lds_dwordx4 v[172:173], off
	v_lshl_add_u64 v[172:173], v[220:221], 0, s[8:9]
	s_mov_b32 m0, s33
	s_nop 0
	global_load_lds_dwordx4 v[172:173], off
	v_lshl_add_u64 v[172:173], v[222:223], 0, s[8:9]
	s_mov_b32 m0, s34
	s_nop 0
	global_load_lds_dwordx4 v[172:173], off
	s_waitcnt vmcnt(8)
	s_waitcnt lgkmcnt(0)
	s_barrier
	s_waitcnt lgkmcnt(0)
	v_mfma_f32_16x16x32_bf16 v[60:63], v[128:131], v[186:189], v[60:63]
	v_mfma_f32_16x16x32_bf16 v[56:59], v[136:139], v[186:189], v[56:59]
	v_mfma_f32_16x16x32_bf16 v[52:55], v[128:131], v[196:199], v[52:55]
	v_mfma_f32_16x16x32_bf16 v[48:51], v[136:139], v[196:199], v[48:51]
	v_mfma_f32_16x16x32_bf16 v[40:43], v[128:131], v[204:207], v[40:43]
	v_mfma_f32_16x16x32_bf16 v[28:31], v[136:139], v[204:207], v[28:31]
	v_mfma_f32_16x16x32_bf16 v[16:19], v[128:131], v[212:215], v[16:19]
	v_mfma_f32_16x16x32_bf16 v[8:11], v[136:139], v[212:215], v[8:11]
	v_mfma_f32_16x16x32_bf16 v[60:63], v[132:135], v[192:195], v[60:63]
	v_mfma_f32_16x16x32_bf16 v[56:59], v[140:143], v[192:195], v[56:59]
	v_mfma_f32_16x16x32_bf16 v[52:55], v[132:135], v[200:203], v[52:55]
	v_mfma_f32_16x16x32_bf16 v[48:51], v[140:143], v[200:203], v[48:51]
	v_mfma_f32_16x16x32_bf16 v[40:43], v[132:135], v[208:211], v[40:43]
	v_mfma_f32_16x16x32_bf16 v[28:31], v[140:143], v[208:211], v[28:31]
	v_mfma_f32_16x16x32_bf16 v[16:19], v[132:135], v[216:219], v[16:19]
	v_mfma_f32_16x16x32_bf16 v[8:11], v[140:143], v[216:219], v[8:11]
	v_mfma_f32_16x16x32_bf16 v[44:47], v[144:147], v[186:189], v[44:47]
	v_mfma_f32_16x16x32_bf16 v[36:39], v[164:167], v[186:189], v[36:39]
	v_mfma_f32_16x16x32_bf16 v[32:35], v[144:147], v[196:199], v[32:35]
	v_mfma_f32_16x16x32_bf16 v[24:27], v[164:167], v[196:199], v[24:27]
	v_mfma_f32_16x16x32_bf16 v[20:23], v[144:147], v[204:207], v[20:23]
	v_mfma_f32_16x16x32_bf16 v[12:15], v[164:167], v[204:207], v[12:15]
	v_mfma_f32_16x16x32_bf16 v[4:7], v[144:147], v[212:215], v[4:7]
	v_mfma_f32_16x16x32_bf16 v[0:3], v[164:167], v[212:215], v[0:3]
	v_mfma_f32_16x16x32_bf16 v[44:47], v[148:151], v[192:195], v[44:47]
	v_mfma_f32_16x16x32_bf16 v[36:39], v[168:171], v[192:195], v[36:39]
	v_mfma_f32_16x16x32_bf16 v[32:35], v[148:151], v[200:203], v[32:35]
	v_mfma_f32_16x16x32_bf16 v[24:27], v[168:171], v[200:203], v[24:27]
	v_mfma_f32_16x16x32_bf16 v[20:23], v[148:151], v[208:211], v[20:23]
	v_mfma_f32_16x16x32_bf16 v[12:15], v[168:171], v[208:211], v[12:15]
	v_mfma_f32_16x16x32_bf16 v[4:7], v[148:151], v[216:219], v[4:7]
	v_mfma_f32_16x16x32_bf16 v[0:3], v[168:171], v[216:219], v[0:3]
	s_barrier
	s_add_i32 s43, s43, 2
	s_add_u32 s14, s14, 0x100
	s_addc_u32 s15, s15, 0
	s_add_u32 s41, s41, 0x100
	s_addc_u32 s42, s42, 0
	s_cmp_gt_u32 s43, 41
	s_cbranch_scc0 .LBB0_588
	s_and_b64 vcc, exec, s[10:11]
	s_cbranch_vccz .LBB0_591
	s_barrier

.LBB0_782:
	ds_read_b128 v[146:149], v178
	ds_read_b128 v[150:153], v178 offset:1024
	ds_read_b128 v[154:157], v178 offset:2048
	ds_read_b128 v[158:161], v178 offset:3072
	ds_read_b128 v[162:165], v179
	ds_read_b128 v[166:169], v179 offset:1024
	ds_read_b128 v[170:173], v179 offset:2048
	ds_read_b128 v[186:189], v179 offset:3072
	s_add_u32 s34, s30, 0xfffc0080
	s_addc_u32 s35, s31, -1
	s_cmp_eq_u32 s57, 12
	s_cselect_b32 s37, s1, s35
	s_cselect_b32 s36, s21, s34
	s_cselect_b32 s35, s23, s56
	s_cselect_b32 s34, s54, s55
	v_lshl_add_u64 v[224:225], s[30:31], 0, v[138:139]
	s_add_i32 m0, s29, 0xc000
	ds_read_b128 v[192:195], v180
	ds_read_b128 v[196:199], v180 offset:1024
	ds_read_b128 v[200:203], v180 offset:2048
	ds_read_b128 v[204:207], v180 offset:3072
	ds_read_b128 v[208:211], v180 offset:4096
	ds_read_b128 v[212:215], v180 offset:5120
	ds_read_b128 v[216:219], v180 offset:6144
	ds_read_b128 v[220:223], v180 offset:7168
	global_load_lds_dwordx4 v[224:225], off
	v_lshl_add_u64 v[224:225], s[30:31], 0, v[140:141]
	s_add_i32 m0, s29, 0xe000
	s_nop 0
	global_load_lds_dwordx4 v[224:225], off
	s_waitcnt vmcnt(8)
	s_waitcnt lgkmcnt(0)
	s_barrier
	s_waitcnt lgkmcnt(0)
	v_mfma_f32_16x16x32_bf16 v[124:127], v[146:149], v[192:195], v[124:127]
	v_mfma_f32_16x16x32_bf16 v[120:123], v[154:157], v[192:195], v[120:123]
	v_mfma_f32_16x16x32_bf16 v[116:119], v[146:149], v[200:203], v[116:119]
	v_mfma_f32_16x16x32_bf16 v[108:111], v[154:157], v[200:203], v[108:111]
	v_mfma_f32_16x16x32_bf16 v[100:103], v[146:149], v[208:211], v[100:103]
	v_mfma_f32_16x16x32_bf16 v[92:95], v[154:157], v[208:211], v[92:95]
	v_mfma_f32_16x16x32_bf16 v[84:87], v[146:149], v[216:219], v[84:87]
	v_mfma_f32_16x16x32_bf16 v[76:79], v[154:157], v[216:219], v[76:79]
	v_mfma_f32_16x16x32_bf16 v[124:127], v[150:153], v[196:199], v[124:127]
	v_mfma_f32_16x16x32_bf16 v[120:123], v[158:161], v[196:199], v[120:123]
	v_mfma_f32_16x16x32_bf16 v[116:119], v[150:153], v[204:207], v[116:119]
	v_mfma_f32_16x16x32_bf16 v[108:111], v[158:161], v[204:207], v[108:111]
	v_mfma_f32_16x16x32_bf16 v[100:103], v[150:153], v[212:215], v[100:103]
	v_mfma_f32_16x16x32_bf16 v[92:95], v[158:161], v[212:215], v[92:95]
	v_mfma_f32_16x16x32_bf16 v[84:87], v[150:153], v[220:223], v[84:87]
	v_mfma_f32_16x16x32_bf16 v[76:79], v[158:161], v[220:223], v[76:79]
	v_mfma_f32_16x16x32_bf16 v[112:115], v[162:165], v[192:195], v[112:115]
	v_mfma_f32_16x16x32_bf16 v[104:107], v[170:173], v[192:195], v[104:107]
	v_mfma_f32_16x16x32_bf16 v[96:99], v[162:165], v[200:203], v[96:99]
	v_mfma_f32_16x16x32_bf16 v[88:91], v[170:173], v[200:203], v[88:91]
	v_mfma_f32_16x16x32_bf16 v[80:83], v[162:165], v[208:211], v[80:83]
	v_mfma_f32_16x16x32_bf16 v[72:75], v[170:173], v[208:211], v[72:75]
	v_mfma_f32_16x16x32_bf16 v[68:71], v[162:165], v[216:219], v[68:71]
	v_mfma_f32_16x16x32_bf16 v[64:67], v[170:173], v[216:219], v[64:67]
	v_mfma_f32_16x16x32_bf16 v[112:115], v[166:169], v[196:199], v[112:115]
	v_mfma_f32_16x16x32_bf16 v[104:107], v[186:189], v[196:199], v[104:107]
	v_mfma_f32_16x16x32_bf16 v[96:99], v[166:169], v[204:207], v[96:99]
	v_mfma_f32_16x16x32_bf16 v[88:91], v[186:189], v[204:207], v[88:91]
	v_mfma_f32_16x16x32_bf16 v[80:83], v[166:169], v[212:215], v[80:83]
	v_mfma_f32_16x16x32_bf16 v[72:75], v[186:189], v[212:215], v[72:75]
	v_mfma_f32_16x16x32_bf16 v[68:71], v[166:169], v[220:223], v[68:71]
	v_mfma_f32_16x16x32_bf16 v[64:67], v[186:189], v[220:223], v[64:67]
	s_barrier
	s_add_i32 s58, s47, s33
	v_lshl_add_u64 v[224:225], s[34:35], 0, v[130:131]
	s_mov_b32 m0, s58
	ds_read_b128 v[192:195], v180 offset:16384
	ds_read_b128 v[196:199], v180 offset:17408
	ds_read_b128 v[200:203], v180 offset:18432
	ds_read_b128 v[204:207], v180 offset:19456
	ds_read_b128 v[208:211], v180 offset:20480
	ds_read_b128 v[212:215], v180 offset:21504
	ds_read_b128 v[216:219], v180 offset:22528
	ds_read_b128 v[220:223], v180 offset:23552
	global_load_lds_dwordx4 v[224:225], off
	s_add_i32 m0, s58, 0x2000
	s_add_u32 s58, s34, 0x40000
	v_lshl_add_u64 v[226:227], s[34:35], 0, v[134:135]
	s_addc_u32 s59, s35, 0
	s_add_i32 s60, s48, s33
	global_load_lds_dwordx4 v[226:227], off
	v_lshl_add_u64 v[228:229], s[58:59], 0, v[130:131]
	s_mov_b32 m0, s60
	v_lshl_add_u64 v[230:231], s[36:37], 0, v[132:133]
	global_load_lds_dwordx4 v[228:229], off
	v_lshl_add_u64 v[228:229], s[58:59], 0, v[134:135]
	s_add_i32 m0, s60, 0x2000
	s_nop 0
	global_load_lds_dwordx4 v[228:229], off
	v_lshl_add_u64 v[228:229], s[36:37], 0, v[128:129]
	s_mov_b32 m0, s29
	s_nop 0
	global_load_lds_dwordx4 v[228:229], off
	s_mov_b32 m0, s40
	s_nop 0
	global_load_lds_dwordx4 v[230:231], off
	s_waitcnt vmcnt(8)
	s_waitcnt lgkmcnt(0)
	s_barrier
	s_waitcnt lgkmcnt(0)
	v_mfma_f32_16x16x32_bf16 v[60:63], v[146:149], v[192:195], v[60:63]
	v_mfma_f32_16x16x32_bf16 v[56:59], v[154:157], v[192:195], v[56:59]
	v_mfma_f32_16x16x32_bf16 v[52:55], v[146:149], v[200:203], v[52:55]
	v_mfma_f32_16x16x32_bf16 v[44:47], v[154:157], v[200:203], v[44:47]
	v_mfma_f32_16x16x32_bf16 v[36:39], v[146:149], v[208:211], v[36:39]
	v_mfma_f32_16x16x32_bf16 v[28:31], v[154:157], v[208:211], v[28:31]
	v_mfma_f32_16x16x32_bf16 v[20:23], v[146:149], v[216:219], v[20:23]
	v_mfma_f32_16x16x32_bf16 v[12:15], v[154:157], v[216:219], v[12:15]
	v_mfma_f32_16x16x32_bf16 v[60:63], v[150:153], v[196:199], v[60:63]
	v_mfma_f32_16x16x32_bf16 v[56:59], v[158:161], v[196:199], v[56:59]
	v_mfma_f32_16x16x32_bf16 v[52:55], v[150:153], v[204:207], v[52:55]
	v_mfma_f32_16x16x32_bf16 v[44:47], v[158:161], v[204:207], v[44:47]
	v_mfma_f32_16x16x32_bf16 v[36:39], v[150:153], v[212:215], v[36:39]
	v_mfma_f32_16x16x32_bf16 v[28:31], v[158:161], v[212:215], v[28:31]
	v_mfma_f32_16x16x32_bf16 v[20:23], v[150:153], v[220:223], v[20:23]
	v_mfma_f32_16x16x32_bf16 v[12:15], v[158:161], v[220:223], v[12:15]
	v_mfma_f32_16x16x32_bf16 v[48:51], v[162:165], v[192:195], v[48:51]
	v_mfma_f32_16x16x32_bf16 v[40:43], v[170:173], v[192:195], v[40:43]
	v_mfma_f32_16x16x32_bf16 v[32:35], v[162:165], v[200:203], v[32:35]
	v_mfma_f32_16x16x32_bf16 v[24:27], v[170:173], v[200:203], v[24:27]
	v_mfma_f32_16x16x32_bf16 v[16:19], v[162:165], v[208:211], v[16:19]
	v_mfma_f32_16x16x32_bf16 v[8:11], v[170:173], v[208:211], v[8:11]
	v_mfma_f32_16x16x32_bf16 v[4:7], v[162:165], v[216:219], v[4:7]
	v_mfma_f32_16x16x32_bf16 v[0:3], v[170:173], v[216:219], v[0:3]
	v_mfma_f32_16x16x32_bf16 v[48:51], v[166:169], v[196:199], v[48:51]
	v_mfma_f32_16x16x32_bf16 v[40:43], v[186:189], v[196:199], v[40:43]
	v_mfma_f32_16x16x32_bf16 v[32:35], v[166:169], v[204:207], v[32:35]
	v_mfma_f32_16x16x32_bf16 v[24:27], v[186:189], v[204:207], v[24:27]
	v_mfma_f32_16x16x32_bf16 v[16:19], v[166:169], v[212:215], v[16:19]
	v_mfma_f32_16x16x32_bf16 v[8:11], v[186:189], v[212:215], v[8:11]
	v_mfma_f32_16x16x32_bf16 v[4:7], v[166:169], v[220:223], v[4:7]
	v_mfma_f32_16x16x32_bf16 v[0:3], v[186:189], v[220:223], v[0:3]
	s_barrier
	s_add_i32 s58, 0, 0x18000
	v_add_u32_e32 v136, s58, v175
	s_add_i32 s59, 0, 0x1c000
	ds_read_b128 v[146:149], v136
	ds_read_b128 v[150:153], v136 offset:1024
	ds_read_b128 v[154:157], v136 offset:2048
	ds_read_b128 v[158:161], v136 offset:3072
	v_add_u32_e32 v136, s59, v175
	ds_read_b128 v[162:165], v136
	ds_read_b128 v[166:169], v136 offset:1024
	ds_read_b128 v[170:173], v136 offset:2048
	ds_read_b128 v[186:189], v136 offset:3072
	s_add_u32 s36, s36, 0x40000
	s_addc_u32 s37, s37, 0
	s_mov_b32 m0, s41
	v_lshl_add_u64 v[232:233], s[36:37], 0, v[128:129]
	ds_read_b128 v[192:195], v180 offset:32768
	ds_read_b128 v[196:199], v180 offset:33792
	ds_read_b128 v[200:203], v180 offset:34816
	ds_read_b128 v[204:207], v180 offset:35840
	ds_read_b128 v[208:211], v180 offset:36864
	ds_read_b128 v[212:215], v180 offset:37888
	ds_read_b128 v[216:219], v180 offset:38912
	ds_read_b128 v[220:223], v180 offset:39936
	global_load_lds_dwordx4 v[232:233], off
	v_lshl_add_u64 v[232:233], s[36:37], 0, v[132:133]
	s_mov_b32 m0, s42
	s_nop 0
	global_load_lds_dwordx4 v[232:233], off
	s_waitcnt vmcnt(8)
	s_waitcnt lgkmcnt(0)
	s_barrier
	s_waitcnt lgkmcnt(0)
	v_mfma_f32_16x16x32_bf16 v[124:127], v[146:149], v[192:195], v[124:127]
	v_mfma_f32_16x16x32_bf16 v[120:123], v[154:157], v[192:195], v[120:123]
	v_mfma_f32_16x16x32_bf16 v[116:119], v[146:149], v[200:203], v[116:119]
	v_mfma_f32_16x16x32_bf16 v[108:111], v[154:157], v[200:203], v[108:111]
	v_mfma_f32_16x16x32_bf16 v[100:103], v[146:149], v[208:211], v[100:103]
	v_mfma_f32_16x16x32_bf16 v[92:95], v[154:157], v[208:211], v[92:95]
	v_mfma_f32_16x16x32_bf16 v[84:87], v[146:149], v[216:219], v[84:87]
	v_mfma_f32_16x16x32_bf16 v[76:79], v[154:157], v[216:219], v[76:79]
	v_mfma_f32_16x16x32_bf16 v[124:127], v[150:153], v[196:199], v[124:127]
	v_mfma_f32_16x16x32_bf16 v[120:123], v[158:161], v[196:199], v[120:123]
	v_mfma_f32_16x16x32_bf16 v[116:119], v[150:153], v[204:207], v[116:119]
	v_mfma_f32_16x16x32_bf16 v[108:111], v[158:161], v[204:207], v[108:111]
	v_mfma_f32_16x16x32_bf16 v[100:103], v[150:153], v[212:215], v[100:103]
	v_mfma_f32_16x16x32_bf16 v[92:95], v[158:161], v[212:215], v[92:95]
	v_mfma_f32_16x16x32_bf16 v[84:87], v[150:153], v[220:223], v[84:87]
	v_mfma_f32_16x16x32_bf16 v[76:79], v[158:161], v[220:223], v[76:79]
	v_mfma_f32_16x16x32_bf16 v[112:115], v[162:165], v[192:195], v[112:115]
	v_mfma_f32_16x16x32_bf16 v[104:107], v[170:173], v[192:195], v[104:107]
	v_mfma_f32_16x16x32_bf16 v[96:99], v[162:165], v[200:203], v[96:99]
	v_mfma_f32_16x16x32_bf16 v[88:91], v[170:173], v[200:203], v[88:91]
	v_mfma_f32_16x16x32_bf16 v[80:83], v[162:165], v[208:211], v[80:83]
	v_mfma_f32_16x16x32_bf16 v[72:75], v[170:173], v[208:211], v[72:75]
	v_mfma_f32_16x16x32_bf16 v[68:71], v[162:165], v[216:219], v[68:71]
	v_mfma_f32_16x16x32_bf16 v[64:67], v[170:173], v[216:219], v[64:67]
	v_mfma_f32_16x16x32_bf16 v[112:115], v[166:169], v[196:199], v[112:115]
	v_mfma_f32_16x16x32_bf16 v[104:107], v[186:189], v[196:199], v[104:107]
	v_mfma_f32_16x16x32_bf16 v[96:99], v[166:169], v[204:207], v[96:99]
	v_mfma_f32_16x16x32_bf16 v[88:91], v[186:189], v[204:207], v[88:91]
	v_mfma_f32_16x16x32_bf16 v[80:83], v[166:169], v[212:215], v[80:83]
	v_mfma_f32_16x16x32_bf16 v[72:75], v[186:189], v[212:215], v[72:75]
	v_mfma_f32_16x16x32_bf16 v[68:71], v[166:169], v[220:223], v[68:71]
	v_mfma_f32_16x16x32_bf16 v[64:67], v[186:189], v[220:223], v[64:67]
	s_barrier
	s_add_i32 s36, s58, s33
	v_lshl_add_u64 v[224:225], v[224:225], 0, s[10:11]
	s_mov_b32 m0, s36
	ds_read_b128 v[192:195], v180 offset:49152
	ds_read_b128 v[196:199], v180 offset:50176
	ds_read_b128 v[200:203], v180 offset:51200
	ds_read_b128 v[204:207], v180 offset:52224
	ds_read_b128 v[208:211], v180 offset:53248
	ds_read_b128 v[212:215], v180 offset:54272
	ds_read_b128 v[216:219], v180 offset:55296
	ds_read_b128 v[220:223], v180 offset:56320
	global_load_lds_dwordx4 v[224:225], off
	s_add_i32 m0, s36, 0x2000
	s_add_u32 s34, s34, 0x40080
	v_lshl_add_u64 v[224:225], v[226:227], 0, s[10:11]
	s_addc_u32 s35, s35, 0
	s_add_i32 s36, s59, s33
	global_load_lds_dwordx4 v[224:225], off
	v_lshl_add_u64 v[224:225], s[34:35], 0, v[130:131]
	s_mov_b32 m0, s36
	s_nop 0
	global_load_lds_dwordx4 v[224:225], off
	v_lshl_add_u64 v[224:225], s[34:35], 0, v[134:135]
	s_add_i32 m0, s36, 0x2000
	s_nop 0
	global_load_lds_dwordx4 v[224:225], off
	v_lshl_add_u64 v[224:225], v[228:229], 0, s[10:11]
	s_mov_b32 m0, s45
	s_nop 0
	global_load_lds_dwordx4 v[224:225], off
	v_lshl_add_u64 v[224:225], v[230:231], 0, s[10:11]
	s_mov_b32 m0, s46
	s_nop 0
	global_load_lds_dwordx4 v[224:225], off
	s_waitcnt vmcnt(8)
	s_waitcnt lgkmcnt(0)
	s_barrier
	s_waitcnt lgkmcnt(0)
	v_mfma_f32_16x16x32_bf16 v[60:63], v[146:149], v[192:195], v[60:63]
	v_mfma_f32_16x16x32_bf16 v[56:59], v[154:157], v[192:195], v[56:59]
	v_mfma_f32_16x16x32_bf16 v[52:55], v[146:149], v[200:203], v[52:55]
	v_mfma_f32_16x16x32_bf16 v[44:47], v[154:157], v[200:203], v[44:47]
	v_mfma_f32_16x16x32_bf16 v[36:39], v[146:149], v[208:211], v[36:39]
	v_mfma_f32_16x16x32_bf16 v[28:31], v[154:157], v[208:211], v[28:31]
	v_mfma_f32_16x16x32_bf16 v[20:23], v[146:149], v[216:219], v[20:23]
	v_mfma_f32_16x16x32_bf16 v[12:15], v[154:157], v[216:219], v[12:15]
	v_mfma_f32_16x16x32_bf16 v[60:63], v[150:153], v[196:199], v[60:63]
	v_mfma_f32_16x16x32_bf16 v[56:59], v[158:161], v[196:199], v[56:59]
	v_mfma_f32_16x16x32_bf16 v[52:55], v[150:153], v[204:207], v[52:55]
	v_mfma_f32_16x16x32_bf16 v[44:47], v[158:161], v[204:207], v[44:47]
	v_mfma_f32_16x16x32_bf16 v[36:39], v[150:153], v[212:215], v[36:39]
	v_mfma_f32_16x16x32_bf16 v[28:31], v[158:161], v[212:215], v[28:31]
	v_mfma_f32_16x16x32_bf16 v[20:23], v[150:153], v[220:223], v[20:23]
	v_mfma_f32_16x16x32_bf16 v[12:15], v[158:161], v[220:223], v[12:15]
	v_mfma_f32_16x16x32_bf16 v[48:51], v[162:165], v[192:195], v[48:51]
	v_mfma_f32_16x16x32_bf16 v[40:43], v[170:173], v[192:195], v[40:43]
	v_mfma_f32_16x16x32_bf16 v[32:35], v[162:165], v[200:203], v[32:35]
	v_mfma_f32_16x16x32_bf16 v[24:27], v[170:173], v[200:203], v[24:27]
	v_mfma_f32_16x16x32_bf16 v[16:19], v[162:165], v[208:211], v[16:19]
	v_mfma_f32_16x16x32_bf16 v[8:11], v[170:173], v[208:211], v[8:11]
	v_mfma_f32_16x16x32_bf16 v[4:7], v[162:165], v[216:219], v[4:7]
	v_mfma_f32_16x16x32_bf16 v[0:3], v[170:173], v[216:219], v[0:3]
	v_mfma_f32_16x16x32_bf16 v[48:51], v[166:169], v[196:199], v[48:51]
	v_mfma_f32_16x16x32_bf16 v[40:43], v[186:189], v[196:199], v[40:43]
	v_mfma_f32_16x16x32_bf16 v[32:35], v[166:169], v[204:207], v[32:35]
	v_mfma_f32_16x16x32_bf16 v[24:27], v[186:189], v[204:207], v[24:27]
	v_mfma_f32_16x16x32_bf16 v[16:19], v[166:169], v[212:215], v[16:19]
	v_mfma_f32_16x16x32_bf16 v[8:11], v[186:189], v[212:215], v[8:11]
	v_mfma_f32_16x16x32_bf16 v[4:7], v[166:169], v[220:223], v[4:7]
	v_mfma_f32_16x16x32_bf16 v[0:3], v[186:189], v[220:223], v[0:3]
	s_barrier
	s_add_i32 s57, s57, 2
	s_add_u32 s30, s30, 0x100
	s_addc_u32 s31, s31, 0
	s_add_u32 s55, s55, 0x100
	s_addc_u32 s56, s56, 0
	s_cmp_gt_u32 s57, 13
	s_cbranch_scc0 .LBB0_782
	s_and_b64 vcc, exec, s[12:13]
	s_cbranch_vccz .LBB0_785
	s_barrier

.LBB0_980:
	ds_read_b128 v[80:83], v194
	ds_read_b128 v[84:87], v194 offset:1024
	ds_read_b128 v[88:91], v194 offset:2048
	ds_read_b128 v[96:99], v194 offset:3072
	ds_read_b128 v[144:147], v195
	ds_read_b128 v[148:151], v195 offset:1024
	ds_read_b128 v[152:155], v195 offset:2048
	ds_read_b128 v[156:159], v195 offset:3072
	s_add_u32 s30, s28, 0xfffc0080
	s_addc_u32 s31, s29, -1
	s_cmp_eq_u32 s55, 12
	s_cselect_b32 s35, s19, s31
	s_cselect_b32 s34, s25, s30
	s_cselect_b32 s31, s17, s54
	s_cselect_b32 s30, s52, s53
	v_lshl_add_u64 v[188:189], s[28:29], 0, v[164:165]
	s_add_i32 m0, s27, 0xc000
	ds_read_b128 v[172:175], v196
	ds_read_b128 v[176:179], v196 offset:1024
	ds_read_b128 v[180:183], v196 offset:2048
	ds_read_b128 v[184:187], v196 offset:3072
	ds_read_b128 v[198:201], v196 offset:4096
	ds_read_b128 v[202:205], v196 offset:5120
	ds_read_b128 v[206:209], v196 offset:6144
	ds_read_b128 v[210:213], v196 offset:7168
	global_load_lds_dwordx4 v[188:189], off
	v_lshl_add_u64 v[188:189], s[28:29], 0, v[166:167]
	s_add_i32 m0, s27, 0xe000
	s_nop 0
	global_load_lds_dwordx4 v[188:189], off
	s_waitcnt vmcnt(8)
	s_waitcnt lgkmcnt(0)
	s_barrier
	s_waitcnt lgkmcnt(0)
	v_mfma_f32_16x16x32_bf16 v[140:143], v[80:83], v[172:175], v[140:143]
	v_mfma_f32_16x16x32_bf16 v[136:139], v[88:91], v[172:175], v[136:139]
	v_mfma_f32_16x16x32_bf16 v[124:127], v[80:83], v[180:183], v[124:127]
	v_mfma_f32_16x16x32_bf16 v[120:123], v[88:91], v[180:183], v[120:123]
	v_mfma_f32_16x16x32_bf16 v[108:111], v[80:83], v[198:201], v[108:111]
	v_mfma_f32_16x16x32_bf16 v[104:107], v[88:91], v[198:201], v[104:107]
	v_mfma_f32_16x16x32_bf16 v[76:79], v[80:83], v[206:209], v[76:79]
	v_mfma_f32_16x16x32_bf16 v[72:75], v[88:91], v[206:209], v[72:75]
	v_mfma_f32_16x16x32_bf16 v[140:143], v[84:87], v[176:179], v[140:143]
	v_mfma_f32_16x16x32_bf16 v[136:139], v[96:99], v[176:179], v[136:139]
	v_mfma_f32_16x16x32_bf16 v[124:127], v[84:87], v[184:187], v[124:127]
	v_mfma_f32_16x16x32_bf16 v[120:123], v[96:99], v[184:187], v[120:123]
	v_mfma_f32_16x16x32_bf16 v[108:111], v[84:87], v[202:205], v[108:111]
	v_mfma_f32_16x16x32_bf16 v[104:107], v[96:99], v[202:205], v[104:107]
	v_mfma_f32_16x16x32_bf16 v[76:79], v[84:87], v[210:213], v[76:79]
	v_mfma_f32_16x16x32_bf16 v[72:75], v[96:99], v[210:213], v[72:75]
	v_mfma_f32_16x16x32_bf16 v[132:135], v[144:147], v[172:175], v[132:135]
	v_mfma_f32_16x16x32_bf16 v[128:131], v[152:155], v[172:175], v[128:131]
	v_mfma_f32_16x16x32_bf16 v[116:119], v[144:147], v[180:183], v[116:119]
	v_mfma_f32_16x16x32_bf16 v[112:115], v[152:155], v[180:183], v[112:115]
	v_mfma_f32_16x16x32_bf16 v[100:103], v[144:147], v[198:201], v[100:103]
	v_mfma_f32_16x16x32_bf16 v[92:95], v[152:155], v[198:201], v[92:95]
	v_mfma_f32_16x16x32_bf16 v[68:71], v[144:147], v[206:209], v[68:71]
	v_mfma_f32_16x16x32_bf16 v[64:67], v[152:155], v[206:209], v[64:67]
	v_mfma_f32_16x16x32_bf16 v[132:135], v[148:151], v[176:179], v[132:135]
	v_mfma_f32_16x16x32_bf16 v[128:131], v[156:159], v[176:179], v[128:131]
	v_mfma_f32_16x16x32_bf16 v[116:119], v[148:151], v[184:187], v[116:119]
	v_mfma_f32_16x16x32_bf16 v[112:115], v[156:159], v[184:187], v[112:115]
	v_mfma_f32_16x16x32_bf16 v[100:103], v[148:151], v[202:205], v[100:103]
	v_mfma_f32_16x16x32_bf16 v[92:95], v[156:159], v[202:205], v[92:95]
	v_mfma_f32_16x16x32_bf16 v[68:71], v[148:151], v[210:213], v[68:71]
	v_mfma_f32_16x16x32_bf16 v[64:67], v[156:159], v[210:213], v[64:67]
	s_barrier
	s_add_i32 s56, s50, s37
	v_lshl_add_u64 v[188:189], s[30:31], 0, v[160:161]
	s_mov_b32 m0, s56
	ds_read_b128 v[172:175], v196 offset:16384
	ds_read_b128 v[176:179], v196 offset:17408
	ds_read_b128 v[180:183], v196 offset:18432
	ds_read_b128 v[184:187], v196 offset:19456
	ds_read_b128 v[198:201], v196 offset:20480
	ds_read_b128 v[202:205], v196 offset:21504
	ds_read_b128 v[206:209], v196 offset:22528
	ds_read_b128 v[210:213], v196 offset:23552
	global_load_lds_dwordx4 v[188:189], off
	s_add_i32 m0, s56, 0x2000
	s_add_u32 s56, s30, 0x40000
	v_lshl_add_u64 v[214:215], s[30:31], 0, v[162:163]
	s_addc_u32 s57, s31, 0
	s_add_i32 s58, s51, s37
	global_load_lds_dwordx4 v[214:215], off
	v_lshl_add_u64 v[216:217], s[56:57], 0, v[160:161]
	s_mov_b32 m0, s58
	v_lshl_add_u64 v[218:219], s[34:35], 0, v[162:163]
	global_load_lds_dwordx4 v[216:217], off
	v_lshl_add_u64 v[216:217], s[56:57], 0, v[162:163]
	s_add_i32 m0, s58, 0x2000
	s_nop 0
	global_load_lds_dwordx4 v[216:217], off
	v_lshl_add_u64 v[216:217], s[34:35], 0, v[160:161]
	s_mov_b32 m0, s27
	s_nop 0
	global_load_lds_dwordx4 v[216:217], off
	s_mov_b32 m0, s38
	s_nop 0
	global_load_lds_dwordx4 v[218:219], off
	s_waitcnt vmcnt(8)
	s_waitcnt lgkmcnt(0)
	s_barrier
	s_waitcnt lgkmcnt(0)
	v_mfma_f32_16x16x32_bf16 v[60:63], v[80:83], v[172:175], v[60:63]
	v_mfma_f32_16x16x32_bf16 v[56:59], v[88:91], v[172:175], v[56:59]
	v_mfma_f32_16x16x32_bf16 v[44:47], v[80:83], v[180:183], v[44:47]
	v_mfma_f32_16x16x32_bf16 v[40:43], v[88:91], v[180:183], v[40:43]
	v_mfma_f32_16x16x32_bf16 v[28:31], v[80:83], v[198:201], v[28:31]
	v_mfma_f32_16x16x32_bf16 v[24:27], v[88:91], v[198:201], v[24:27]
	v_mfma_f32_16x16x32_bf16 v[12:15], v[80:83], v[206:209], v[12:15]
	v_mfma_f32_16x16x32_bf16 v[8:11], v[88:91], v[206:209], v[8:11]
	v_mfma_f32_16x16x32_bf16 v[60:63], v[84:87], v[176:179], v[60:63]
	v_mfma_f32_16x16x32_bf16 v[56:59], v[96:99], v[176:179], v[56:59]
	v_mfma_f32_16x16x32_bf16 v[44:47], v[84:87], v[184:187], v[44:47]
	v_mfma_f32_16x16x32_bf16 v[40:43], v[96:99], v[184:187], v[40:43]
	v_mfma_f32_16x16x32_bf16 v[28:31], v[84:87], v[202:205], v[28:31]
	v_mfma_f32_16x16x32_bf16 v[24:27], v[96:99], v[202:205], v[24:27]
	v_mfma_f32_16x16x32_bf16 v[12:15], v[84:87], v[210:213], v[12:15]
	v_mfma_f32_16x16x32_bf16 v[8:11], v[96:99], v[210:213], v[8:11]
	v_mfma_f32_16x16x32_bf16 v[52:55], v[144:147], v[172:175], v[52:55]
	v_mfma_f32_16x16x32_bf16 v[48:51], v[152:155], v[172:175], v[48:51]
	v_mfma_f32_16x16x32_bf16 v[36:39], v[144:147], v[180:183], v[36:39]
	v_mfma_f32_16x16x32_bf16 v[32:35], v[152:155], v[180:183], v[32:35]
	v_mfma_f32_16x16x32_bf16 v[20:23], v[144:147], v[198:201], v[20:23]
	v_mfma_f32_16x16x32_bf16 v[16:19], v[152:155], v[198:201], v[16:19]
	v_mfma_f32_16x16x32_bf16 v[4:7], v[144:147], v[206:209], v[4:7]
	v_mfma_f32_16x16x32_bf16 v[0:3], v[152:155], v[206:209], v[0:3]
	v_mfma_f32_16x16x32_bf16 v[52:55], v[148:151], v[176:179], v[52:55]
	v_mfma_f32_16x16x32_bf16 v[48:51], v[156:159], v[176:179], v[48:51]
	v_mfma_f32_16x16x32_bf16 v[36:39], v[148:151], v[184:187], v[36:39]
	v_mfma_f32_16x16x32_bf16 v[32:35], v[156:159], v[184:187], v[32:35]
	v_mfma_f32_16x16x32_bf16 v[20:23], v[148:151], v[202:205], v[20:23]
	v_mfma_f32_16x16x32_bf16 v[16:19], v[156:159], v[202:205], v[16:19]
	v_mfma_f32_16x16x32_bf16 v[4:7], v[148:151], v[210:213], v[4:7]
	v_mfma_f32_16x16x32_bf16 v[0:3], v[156:159], v[210:213], v[0:3]
	s_barrier
	s_add_i32 s56, 0, 0x18000
	s_add_i32 s57, 0, 0x1c000
	v_add_u32_e32 v96, s56, v192
	v_add_u32_e32 v156, s57, v192
	ds_read_b128 v[80:83], v96
	ds_read_b128 v[84:87], v96 offset:1024
	ds_read_b128 v[88:91], v96 offset:2048
	ds_read_b128 v[96:99], v96 offset:3072
	ds_read_b128 v[144:147], v156
	ds_read_b128 v[148:151], v156 offset:1024
	ds_read_b128 v[152:155], v156 offset:2048
	ds_read_b128 v[156:159], v156 offset:3072
	s_add_u32 s34, s34, 0x40000
	s_addc_u32 s35, s35, 0
	s_mov_b32 m0, s39
	v_lshl_add_u64 v[220:221], s[34:35], 0, v[160:161]
	ds_read_b128 v[172:175], v196 offset:32768
	ds_read_b128 v[176:179], v196 offset:33792
	ds_read_b128 v[180:183], v196 offset:34816
	ds_read_b128 v[184:187], v196 offset:35840
	ds_read_b128 v[198:201], v196 offset:36864
	ds_read_b128 v[202:205], v196 offset:37888
	ds_read_b128 v[206:209], v196 offset:38912
	ds_read_b128 v[210:213], v196 offset:39936
	global_load_lds_dwordx4 v[220:221], off
	v_lshl_add_u64 v[220:221], s[34:35], 0, v[162:163]
	s_mov_b32 m0, s40
	s_nop 0
	global_load_lds_dwordx4 v[220:221], off
	s_waitcnt vmcnt(8)
	s_waitcnt lgkmcnt(0)
	s_barrier
	s_waitcnt lgkmcnt(0)
	v_mfma_f32_16x16x32_bf16 v[140:143], v[80:83], v[172:175], v[140:143]
	v_mfma_f32_16x16x32_bf16 v[136:139], v[88:91], v[172:175], v[136:139]
	v_mfma_f32_16x16x32_bf16 v[124:127], v[80:83], v[180:183], v[124:127]
	v_mfma_f32_16x16x32_bf16 v[120:123], v[88:91], v[180:183], v[120:123]
	v_mfma_f32_16x16x32_bf16 v[108:111], v[80:83], v[198:201], v[108:111]
	v_mfma_f32_16x16x32_bf16 v[104:107], v[88:91], v[198:201], v[104:107]
	v_mfma_f32_16x16x32_bf16 v[76:79], v[80:83], v[206:209], v[76:79]
	v_mfma_f32_16x16x32_bf16 v[72:75], v[88:91], v[206:209], v[72:75]
	v_mfma_f32_16x16x32_bf16 v[140:143], v[84:87], v[176:179], v[140:143]
	v_mfma_f32_16x16x32_bf16 v[136:139], v[96:99], v[176:179], v[136:139]
	v_mfma_f32_16x16x32_bf16 v[124:127], v[84:87], v[184:187], v[124:127]
	v_mfma_f32_16x16x32_bf16 v[120:123], v[96:99], v[184:187], v[120:123]
	v_mfma_f32_16x16x32_bf16 v[108:111], v[84:87], v[202:205], v[108:111]
	v_mfma_f32_16x16x32_bf16 v[104:107], v[96:99], v[202:205], v[104:107]
	v_mfma_f32_16x16x32_bf16 v[76:79], v[84:87], v[210:213], v[76:79]
	v_mfma_f32_16x16x32_bf16 v[72:75], v[96:99], v[210:213], v[72:75]
	v_mfma_f32_16x16x32_bf16 v[132:135], v[144:147], v[172:175], v[132:135]
	v_mfma_f32_16x16x32_bf16 v[128:131], v[152:155], v[172:175], v[128:131]
	v_mfma_f32_16x16x32_bf16 v[116:119], v[144:147], v[180:183], v[116:119]
	v_mfma_f32_16x16x32_bf16 v[112:115], v[152:155], v[180:183], v[112:115]
	v_mfma_f32_16x16x32_bf16 v[100:103], v[144:147], v[198:201], v[100:103]
	v_mfma_f32_16x16x32_bf16 v[92:95], v[152:155], v[198:201], v[92:95]
	v_mfma_f32_16x16x32_bf16 v[68:71], v[144:147], v[206:209], v[68:71]
	v_mfma_f32_16x16x32_bf16 v[64:67], v[152:155], v[206:209], v[64:67]
	v_mfma_f32_16x16x32_bf16 v[132:135], v[148:151], v[176:179], v[132:135]
	v_mfma_f32_16x16x32_bf16 v[128:131], v[156:159], v[176:179], v[128:131]
	v_mfma_f32_16x16x32_bf16 v[116:119], v[148:151], v[184:187], v[116:119]
	v_mfma_f32_16x16x32_bf16 v[112:115], v[156:159], v[184:187], v[112:115]
	v_mfma_f32_16x16x32_bf16 v[100:103], v[148:151], v[202:205], v[100:103]
	v_mfma_f32_16x16x32_bf16 v[92:95], v[156:159], v[202:205], v[92:95]
	v_mfma_f32_16x16x32_bf16 v[68:71], v[148:151], v[210:213], v[68:71]
	v_mfma_f32_16x16x32_bf16 v[64:67], v[156:159], v[210:213], v[64:67]
	s_barrier
	s_add_i32 s34, s56, s37
	v_lshl_add_u64 v[188:189], v[188:189], 0, s[12:13]
	s_mov_b32 m0, s34
	ds_read_b128 v[172:175], v196 offset:49152
	ds_read_b128 v[176:179], v196 offset:50176
	ds_read_b128 v[180:183], v196 offset:51200
	ds_read_b128 v[184:187], v196 offset:52224
	ds_read_b128 v[198:201], v196 offset:53248
	ds_read_b128 v[202:205], v196 offset:54272
	ds_read_b128 v[206:209], v196 offset:55296
	ds_read_b128 v[210:213], v196 offset:56320
	global_load_lds_dwordx4 v[188:189], off
	s_add_i32 m0, s34, 0x2000
	s_add_u32 s30, s30, 0x40080
	v_lshl_add_u64 v[188:189], v[214:215], 0, s[12:13]
	s_addc_u32 s31, s31, 0
	s_add_i32 s34, s57, s37
	global_load_lds_dwordx4 v[188:189], off
	v_lshl_add_u64 v[188:189], s[30:31], 0, v[160:161]
	s_mov_b32 m0, s34
	s_nop 0
	global_load_lds_dwordx4 v[188:189], off
	v_lshl_add_u64 v[188:189], s[30:31], 0, v[162:163]
	s_add_i32 m0, s34, 0x2000
	s_nop 0
	global_load_lds_dwordx4 v[188:189], off
	v_lshl_add_u64 v[188:189], v[216:217], 0, s[12:13]
	s_mov_b32 m0, s48
	s_nop 0
	global_load_lds_dwordx4 v[188:189], off
	v_lshl_add_u64 v[188:189], v[218:219], 0, s[12:13]
	s_mov_b32 m0, s49
	s_nop 0
	global_load_lds_dwordx4 v[188:189], off
	s_waitcnt vmcnt(8)
	s_waitcnt lgkmcnt(0)
	s_barrier
	s_waitcnt lgkmcnt(0)
	v_mfma_f32_16x16x32_bf16 v[60:63], v[80:83], v[172:175], v[60:63]
	v_mfma_f32_16x16x32_bf16 v[56:59], v[88:91], v[172:175], v[56:59]
	v_mfma_f32_16x16x32_bf16 v[44:47], v[80:83], v[180:183], v[44:47]
	v_mfma_f32_16x16x32_bf16 v[40:43], v[88:91], v[180:183], v[40:43]
	v_mfma_f32_16x16x32_bf16 v[28:31], v[80:83], v[198:201], v[28:31]
	v_mfma_f32_16x16x32_bf16 v[24:27], v[88:91], v[198:201], v[24:27]
	v_mfma_f32_16x16x32_bf16 v[12:15], v[80:83], v[206:209], v[12:15]
	v_mfma_f32_16x16x32_bf16 v[8:11], v[88:91], v[206:209], v[8:11]
	v_mfma_f32_16x16x32_bf16 v[60:63], v[84:87], v[176:179], v[60:63]
	v_mfma_f32_16x16x32_bf16 v[56:59], v[96:99], v[176:179], v[56:59]
	v_mfma_f32_16x16x32_bf16 v[44:47], v[84:87], v[184:187], v[44:47]
	v_mfma_f32_16x16x32_bf16 v[40:43], v[96:99], v[184:187], v[40:43]
	v_mfma_f32_16x16x32_bf16 v[28:31], v[84:87], v[202:205], v[28:31]
	v_mfma_f32_16x16x32_bf16 v[24:27], v[96:99], v[202:205], v[24:27]
	v_mfma_f32_16x16x32_bf16 v[12:15], v[84:87], v[210:213], v[12:15]
	v_mfma_f32_16x16x32_bf16 v[8:11], v[96:99], v[210:213], v[8:11]
	v_mfma_f32_16x16x32_bf16 v[52:55], v[144:147], v[172:175], v[52:55]
	v_mfma_f32_16x16x32_bf16 v[48:51], v[152:155], v[172:175], v[48:51]
	v_mfma_f32_16x16x32_bf16 v[36:39], v[144:147], v[180:183], v[36:39]
	v_mfma_f32_16x16x32_bf16 v[32:35], v[152:155], v[180:183], v[32:35]
	v_mfma_f32_16x16x32_bf16 v[20:23], v[144:147], v[198:201], v[20:23]
	v_mfma_f32_16x16x32_bf16 v[16:19], v[152:155], v[198:201], v[16:19]
	v_mfma_f32_16x16x32_bf16 v[4:7], v[144:147], v[206:209], v[4:7]
	v_mfma_f32_16x16x32_bf16 v[0:3], v[152:155], v[206:209], v[0:3]
	v_mfma_f32_16x16x32_bf16 v[52:55], v[148:151], v[176:179], v[52:55]
	v_mfma_f32_16x16x32_bf16 v[48:51], v[156:159], v[176:179], v[48:51]
	v_mfma_f32_16x16x32_bf16 v[36:39], v[148:151], v[184:187], v[36:39]
	v_mfma_f32_16x16x32_bf16 v[32:35], v[156:159], v[184:187], v[32:35]
	v_mfma_f32_16x16x32_bf16 v[20:23], v[148:151], v[202:205], v[20:23]
	v_mfma_f32_16x16x32_bf16 v[16:19], v[156:159], v[202:205], v[16:19]
	v_mfma_f32_16x16x32_bf16 v[4:7], v[148:151], v[210:213], v[4:7]
	v_mfma_f32_16x16x32_bf16 v[0:3], v[156:159], v[210:213], v[0:3]
	s_barrier
	s_add_i32 s55, s55, 2
	s_add_u32 s28, s28, 0x100
	s_addc_u32 s29, s29, 0
	s_add_u32 s53, s53, 0x100
	s_addc_u32 s54, s54, 0
	s_cmp_gt_u32 s55, 13
	s_cbranch_scc0 .LBB0_980
	s_and_b64 vcc, exec, s[14:15]
	s_cbranch_vccz .LBB0_983
	s_barrier

.LBB0_1071:
	v_add_u32_e32 v158, s47, v165
	v_add_u32_e32 v169, s48, v165
	ds_read_b128 v[112:115], v158
	ds_read_b128 v[120:123], v158 offset:1024
	ds_read_b128 v[154:157], v158 offset:2048
	ds_read_b128 v[158:161], v158 offset:3072
	ds_read_b128 v[170:173], v169
	ds_read_b128 v[174:177], v169 offset:1024
	ds_read_b128 v[178:181], v169 offset:2048
	ds_read_b128 v[182:185], v169 offset:3072
	s_add_u32 s2, s22, 0xfffc0080
	s_addc_u32 s26, s23, -1
	s_and_b64 s[24:25], s[24:25], exec
	s_cselect_b32 s27, s15, s26
	s_cselect_b32 s26, s53, s2
	s_cselect_b32 s25, s13, s60
	s_cselect_b32 s24, s54, s59
	v_lshl_add_u64 v[220:221], s[22:23], 0, v[146:147]
	s_add_i32 m0, s36, 0xc000
	ds_read_b128 v[186:189], v167
	ds_read_b128 v[192:195], v167 offset:1024
	ds_read_b128 v[196:199], v167 offset:2048
	ds_read_b128 v[200:203], v167 offset:3072
	ds_read_b128 v[204:207], v167 offset:4096
	ds_read_b128 v[208:211], v167 offset:5120
	ds_read_b128 v[212:215], v167 offset:6144
	ds_read_b128 v[216:219], v167 offset:7168
	global_load_lds_dwordx4 v[220:221], off
	v_lshl_add_u64 v[220:221], s[22:23], 0, v[148:149]
	s_add_i32 m0, s36, 0xe000
	s_nop 0
	global_load_lds_dwordx4 v[220:221], off
	s_waitcnt vmcnt(8)
	s_waitcnt lgkmcnt(0)
	s_barrier
	s_waitcnt lgkmcnt(0)
	v_mfma_f32_16x16x32_bf16 v[132:135], v[112:115], v[186:189], v[132:135]
	v_mfma_f32_16x16x32_bf16 v[124:127], v[154:157], v[186:189], v[124:127]
	v_mfma_f32_16x16x32_bf16 v[108:111], v[112:115], v[196:199], v[108:111]
	v_mfma_f32_16x16x32_bf16 v[100:103], v[154:157], v[196:199], v[100:103]
	v_mfma_f32_16x16x32_bf16 v[92:95], v[112:115], v[204:207], v[92:95]
	v_mfma_f32_16x16x32_bf16 v[84:87], v[154:157], v[204:207], v[84:87]
	v_mfma_f32_16x16x32_bf16 v[76:79], v[112:115], v[212:215], v[76:79]
	v_mfma_f32_16x16x32_bf16 v[68:71], v[154:157], v[212:215], v[68:71]
	v_mfma_f32_16x16x32_bf16 v[132:135], v[120:123], v[192:195], v[132:135]
	v_mfma_f32_16x16x32_bf16 v[124:127], v[158:161], v[192:195], v[124:127]
	v_mfma_f32_16x16x32_bf16 v[108:111], v[120:123], v[200:203], v[108:111]
	v_mfma_f32_16x16x32_bf16 v[100:103], v[158:161], v[200:203], v[100:103]
	v_mfma_f32_16x16x32_bf16 v[92:95], v[120:123], v[208:211], v[92:95]
	v_mfma_f32_16x16x32_bf16 v[84:87], v[158:161], v[208:211], v[84:87]
	v_mfma_f32_16x16x32_bf16 v[76:79], v[120:123], v[216:219], v[76:79]
	v_mfma_f32_16x16x32_bf16 v[68:71], v[158:161], v[216:219], v[68:71]
	v_mfma_f32_16x16x32_bf16 v[128:131], v[170:173], v[186:189], v[128:131]
	v_mfma_f32_16x16x32_bf16 v[116:119], v[178:181], v[186:189], v[116:119]
	v_mfma_f32_16x16x32_bf16 v[104:107], v[170:173], v[196:199], v[104:107]
	v_mfma_f32_16x16x32_bf16 v[96:99], v[178:181], v[196:199], v[96:99]
	v_mfma_f32_16x16x32_bf16 v[88:91], v[170:173], v[204:207], v[88:91]
	v_mfma_f32_16x16x32_bf16 v[80:83], v[178:181], v[204:207], v[80:83]
	v_mfma_f32_16x16x32_bf16 v[72:75], v[170:173], v[212:215], v[72:75]
	v_mfma_f32_16x16x32_bf16 v[64:67], v[178:181], v[212:215], v[64:67]
	v_mfma_f32_16x16x32_bf16 v[128:131], v[174:177], v[192:195], v[128:131]
	v_mfma_f32_16x16x32_bf16 v[116:119], v[182:185], v[192:195], v[116:119]
	v_mfma_f32_16x16x32_bf16 v[104:107], v[174:177], v[200:203], v[104:107]
	v_mfma_f32_16x16x32_bf16 v[96:99], v[182:185], v[200:203], v[96:99]
	v_mfma_f32_16x16x32_bf16 v[88:91], v[174:177], v[208:211], v[88:91]
	v_mfma_f32_16x16x32_bf16 v[80:83], v[182:185], v[208:211], v[80:83]
	v_mfma_f32_16x16x32_bf16 v[72:75], v[174:177], v[216:219], v[72:75]
	v_mfma_f32_16x16x32_bf16 v[64:67], v[182:185], v[216:219], v[64:67]
	s_barrier
	s_add_i32 s2, s47, s21
	v_lshl_add_u64 v[220:221], s[24:25], 0, v[138:139]
	s_mov_b32 m0, s2
	ds_read_b128 v[186:189], v167 offset:16384
	ds_read_b128 v[192:195], v167 offset:17408
	ds_read_b128 v[196:199], v167 offset:18432
	ds_read_b128 v[200:203], v167 offset:19456
	ds_read_b128 v[204:207], v167 offset:20480
	ds_read_b128 v[208:211], v167 offset:21504
	ds_read_b128 v[212:215], v167 offset:22528
	ds_read_b128 v[216:219], v167 offset:23552
	global_load_lds_dwordx4 v[220:221], off
	s_add_i32 m0, s2, 0x2000
	s_add_u32 s62, s24, 0x40000
	v_lshl_add_u64 v[222:223], s[24:25], 0, v[142:143]
	s_addc_u32 s63, s25, 0
	s_add_i32 s2, s48, s21
	global_load_lds_dwordx4 v[222:223], off
	v_lshl_add_u64 v[224:225], s[62:63], 0, v[138:139]
	s_mov_b32 m0, s2
	v_lshl_add_u64 v[226:227], s[26:27], 0, v[140:141]
	global_load_lds_dwordx4 v[224:225], off
	v_lshl_add_u64 v[224:225], s[62:63], 0, v[142:143]
	s_add_i32 m0, s2, 0x2000
	s_nop 0
	global_load_lds_dwordx4 v[224:225], off
	v_lshl_add_u64 v[224:225], s[26:27], 0, v[136:137]
	s_mov_b32 m0, s36
	s_nop 0
	global_load_lds_dwordx4 v[224:225], off
	s_mov_b32 m0, s37
	s_nop 0
	global_load_lds_dwordx4 v[226:227], off
	s_waitcnt vmcnt(8)
	s_waitcnt lgkmcnt(0)
	s_barrier
	s_waitcnt lgkmcnt(0)
	v_mfma_f32_16x16x32_bf16 v[60:63], v[112:115], v[186:189], v[60:63]
	v_mfma_f32_16x16x32_bf16 v[52:55], v[154:157], v[186:189], v[52:55]
	v_mfma_f32_16x16x32_bf16 v[44:47], v[112:115], v[196:199], v[44:47]
	v_mfma_f32_16x16x32_bf16 v[36:39], v[154:157], v[196:199], v[36:39]
	v_mfma_f32_16x16x32_bf16 v[28:31], v[112:115], v[204:207], v[28:31]
	v_mfma_f32_16x16x32_bf16 v[20:23], v[154:157], v[204:207], v[20:23]
	v_mfma_f32_16x16x32_bf16 v[12:15], v[112:115], v[212:215], v[12:15]
	v_mfma_f32_16x16x32_bf16 v[4:7], v[154:157], v[212:215], v[4:7]
	v_mfma_f32_16x16x32_bf16 v[60:63], v[120:123], v[192:195], v[60:63]
	v_mfma_f32_16x16x32_bf16 v[52:55], v[158:161], v[192:195], v[52:55]
	v_mfma_f32_16x16x32_bf16 v[44:47], v[120:123], v[200:203], v[44:47]
	v_mfma_f32_16x16x32_bf16 v[36:39], v[158:161], v[200:203], v[36:39]
	v_mfma_f32_16x16x32_bf16 v[28:31], v[120:123], v[208:211], v[28:31]
	v_mfma_f32_16x16x32_bf16 v[20:23], v[158:161], v[208:211], v[20:23]
	v_mfma_f32_16x16x32_bf16 v[12:15], v[120:123], v[216:219], v[12:15]
	v_mfma_f32_16x16x32_bf16 v[4:7], v[158:161], v[216:219], v[4:7]
	v_mfma_f32_16x16x32_bf16 v[56:59], v[170:173], v[186:189], v[56:59]
	v_mfma_f32_16x16x32_bf16 v[48:51], v[178:181], v[186:189], v[48:51]
	v_mfma_f32_16x16x32_bf16 v[40:43], v[170:173], v[196:199], v[40:43]
	v_mfma_f32_16x16x32_bf16 v[32:35], v[178:181], v[196:199], v[32:35]
	v_mfma_f32_16x16x32_bf16 v[24:27], v[170:173], v[204:207], v[24:27]
	v_mfma_f32_16x16x32_bf16 v[16:19], v[178:181], v[204:207], v[16:19]
	v_mfma_f32_16x16x32_bf16 v[8:11], v[170:173], v[212:215], v[8:11]
	v_mfma_f32_16x16x32_bf16 v[0:3], v[178:181], v[212:215], v[0:3]
	v_mfma_f32_16x16x32_bf16 v[56:59], v[174:177], v[192:195], v[56:59]
	v_mfma_f32_16x16x32_bf16 v[48:51], v[182:185], v[192:195], v[48:51]
	v_mfma_f32_16x16x32_bf16 v[40:43], v[174:177], v[200:203], v[40:43]
	v_mfma_f32_16x16x32_bf16 v[32:35], v[182:185], v[200:203], v[32:35]
	v_mfma_f32_16x16x32_bf16 v[24:27], v[174:177], v[208:211], v[24:27]
	v_mfma_f32_16x16x32_bf16 v[16:19], v[182:185], v[208:211], v[16:19]
	v_mfma_f32_16x16x32_bf16 v[8:11], v[174:177], v[216:219], v[8:11]
	v_mfma_f32_16x16x32_bf16 v[0:3], v[182:185], v[216:219], v[0:3]
	s_barrier
	s_add_i32 s2, 0, 0x18000
	s_add_i32 s62, 0, 0x1c000
	v_add_u32_e32 v158, s2, v165
	v_add_u32_e32 v169, s62, v165
	ds_read_b128 v[112:115], v158
	ds_read_b128 v[120:123], v158 offset:1024
	ds_read_b128 v[154:157], v158 offset:2048
	ds_read_b128 v[158:161], v158 offset:3072
	ds_read_b128 v[170:173], v169
	ds_read_b128 v[174:177], v169 offset:1024
	ds_read_b128 v[178:181], v169 offset:2048
	ds_read_b128 v[182:185], v169 offset:3072
	s_add_u32 s26, s26, 0x40000
	s_addc_u32 s27, s27, 0
	s_mov_b32 m0, s38
	v_lshl_add_u64 v[228:229], s[26:27], 0, v[136:137]
	ds_read_b128 v[186:189], v167 offset:32768
	ds_read_b128 v[192:195], v167 offset:33792
	ds_read_b128 v[196:199], v167 offset:34816
	ds_read_b128 v[200:203], v167 offset:35840
	ds_read_b128 v[204:207], v167 offset:36864
	ds_read_b128 v[208:211], v167 offset:37888
	ds_read_b128 v[212:215], v167 offset:38912
	ds_read_b128 v[216:219], v167 offset:39936
	global_load_lds_dwordx4 v[228:229], off
	v_lshl_add_u64 v[228:229], s[26:27], 0, v[140:141]
	s_mov_b32 m0, s39
	s_nop 0
	global_load_lds_dwordx4 v[228:229], off
	s_waitcnt vmcnt(8)
	s_waitcnt lgkmcnt(0)
	s_barrier
	s_waitcnt lgkmcnt(0)
	v_mfma_f32_16x16x32_bf16 v[132:135], v[112:115], v[186:189], v[132:135]
	v_mfma_f32_16x16x32_bf16 v[124:127], v[154:157], v[186:189], v[124:127]
	v_mfma_f32_16x16x32_bf16 v[108:111], v[112:115], v[196:199], v[108:111]
	v_mfma_f32_16x16x32_bf16 v[100:103], v[154:157], v[196:199], v[100:103]
	v_mfma_f32_16x16x32_bf16 v[92:95], v[112:115], v[204:207], v[92:95]
	v_mfma_f32_16x16x32_bf16 v[84:87], v[154:157], v[204:207], v[84:87]
	v_mfma_f32_16x16x32_bf16 v[76:79], v[112:115], v[212:215], v[76:79]
	v_mfma_f32_16x16x32_bf16 v[68:71], v[154:157], v[212:215], v[68:71]
	v_mfma_f32_16x16x32_bf16 v[132:135], v[120:123], v[192:195], v[132:135]
	v_mfma_f32_16x16x32_bf16 v[124:127], v[158:161], v[192:195], v[124:127]
	v_mfma_f32_16x16x32_bf16 v[108:111], v[120:123], v[200:203], v[108:111]
	v_mfma_f32_16x16x32_bf16 v[100:103], v[158:161], v[200:203], v[100:103]
	v_mfma_f32_16x16x32_bf16 v[92:95], v[120:123], v[208:211], v[92:95]
	v_mfma_f32_16x16x32_bf16 v[84:87], v[158:161], v[208:211], v[84:87]
	v_mfma_f32_16x16x32_bf16 v[76:79], v[120:123], v[216:219], v[76:79]
	v_mfma_f32_16x16x32_bf16 v[68:71], v[158:161], v[216:219], v[68:71]
	v_mfma_f32_16x16x32_bf16 v[128:131], v[170:173], v[186:189], v[128:131]
	v_mfma_f32_16x16x32_bf16 v[116:119], v[178:181], v[186:189], v[116:119]
	v_mfma_f32_16x16x32_bf16 v[104:107], v[170:173], v[196:199], v[104:107]
	v_mfma_f32_16x16x32_bf16 v[96:99], v[178:181], v[196:199], v[96:99]
	v_mfma_f32_16x16x32_bf16 v[88:91], v[170:173], v[204:207], v[88:91]
	v_mfma_f32_16x16x32_bf16 v[80:83], v[178:181], v[204:207], v[80:83]
	v_mfma_f32_16x16x32_bf16 v[72:75], v[170:173], v[212:215], v[72:75]
	v_mfma_f32_16x16x32_bf16 v[64:67], v[178:181], v[212:215], v[64:67]
	v_mfma_f32_16x16x32_bf16 v[128:131], v[174:177], v[192:195], v[128:131]
	v_mfma_f32_16x16x32_bf16 v[116:119], v[182:185], v[192:195], v[116:119]
	v_mfma_f32_16x16x32_bf16 v[104:107], v[174:177], v[200:203], v[104:107]
	v_mfma_f32_16x16x32_bf16 v[96:99], v[182:185], v[200:203], v[96:99]
	v_mfma_f32_16x16x32_bf16 v[88:91], v[174:177], v[208:211], v[88:91]
	v_mfma_f32_16x16x32_bf16 v[80:83], v[182:185], v[208:211], v[80:83]
	v_mfma_f32_16x16x32_bf16 v[72:75], v[174:177], v[216:219], v[72:75]
	v_mfma_f32_16x16x32_bf16 v[64:67], v[182:185], v[216:219], v[64:67]
	s_barrier
	s_add_i32 s2, s2, s21
	v_lshl_add_u64 v[220:221], v[220:221], 0, s[8:9]
	s_mov_b32 m0, s2
	ds_read_b128 v[186:189], v167 offset:49152
	ds_read_b128 v[192:195], v167 offset:50176
	ds_read_b128 v[196:199], v167 offset:51200
	ds_read_b128 v[200:203], v167 offset:52224
	ds_read_b128 v[204:207], v167 offset:53248
	ds_read_b128 v[208:211], v167 offset:54272
	ds_read_b128 v[212:215], v167 offset:55296
	ds_read_b128 v[216:219], v167 offset:56320
	global_load_lds_dwordx4 v[220:221], off
	s_add_i32 m0, s2, 0x2000
	s_add_u32 s24, s24, 0x40080
	v_lshl_add_u64 v[220:221], v[222:223], 0, s[8:9]
	s_addc_u32 s25, s25, 0
	s_add_i32 s2, s62, s21
	global_load_lds_dwordx4 v[220:221], off
	v_lshl_add_u64 v[220:221], s[24:25], 0, v[138:139]
	s_mov_b32 m0, s2
	s_nop 0
	global_load_lds_dwordx4 v[220:221], off
	v_lshl_add_u64 v[220:221], s[24:25], 0, v[142:143]
	s_add_i32 m0, s2, 0x2000
	s_nop 0
	global_load_lds_dwordx4 v[220:221], off
	v_lshl_add_u64 v[220:221], v[224:225], 0, s[8:9]
	s_mov_b32 m0, s43
	s_nop 0
	global_load_lds_dwordx4 v[220:221], off
	v_lshl_add_u64 v[220:221], v[226:227], 0, s[8:9]
	s_mov_b32 m0, s44
	s_nop 0
	global_load_lds_dwordx4 v[220:221], off
	s_waitcnt vmcnt(8)
	s_waitcnt lgkmcnt(0)
	s_barrier
	s_waitcnt lgkmcnt(0)
	v_mfma_f32_16x16x32_bf16 v[60:63], v[112:115], v[186:189], v[60:63]
	v_mfma_f32_16x16x32_bf16 v[52:55], v[154:157], v[186:189], v[52:55]
	v_mfma_f32_16x16x32_bf16 v[44:47], v[112:115], v[196:199], v[44:47]
	v_mfma_f32_16x16x32_bf16 v[36:39], v[154:157], v[196:199], v[36:39]
	v_mfma_f32_16x16x32_bf16 v[28:31], v[112:115], v[204:207], v[28:31]
	v_mfma_f32_16x16x32_bf16 v[20:23], v[154:157], v[204:207], v[20:23]
	v_mfma_f32_16x16x32_bf16 v[12:15], v[112:115], v[212:215], v[12:15]
	v_mfma_f32_16x16x32_bf16 v[4:7], v[154:157], v[212:215], v[4:7]
	v_mfma_f32_16x16x32_bf16 v[60:63], v[120:123], v[192:195], v[60:63]
	v_mfma_f32_16x16x32_bf16 v[52:55], v[158:161], v[192:195], v[52:55]
	v_mfma_f32_16x16x32_bf16 v[44:47], v[120:123], v[200:203], v[44:47]
	v_mfma_f32_16x16x32_bf16 v[36:39], v[158:161], v[200:203], v[36:39]
	v_mfma_f32_16x16x32_bf16 v[28:31], v[120:123], v[208:211], v[28:31]
	v_mfma_f32_16x16x32_bf16 v[20:23], v[158:161], v[208:211], v[20:23]
	v_mfma_f32_16x16x32_bf16 v[12:15], v[120:123], v[216:219], v[12:15]
	v_mfma_f32_16x16x32_bf16 v[4:7], v[158:161], v[216:219], v[4:7]
	v_mfma_f32_16x16x32_bf16 v[56:59], v[170:173], v[186:189], v[56:59]
	v_mfma_f32_16x16x32_bf16 v[48:51], v[178:181], v[186:189], v[48:51]
	v_mfma_f32_16x16x32_bf16 v[40:43], v[170:173], v[196:199], v[40:43]
	v_mfma_f32_16x16x32_bf16 v[32:35], v[178:181], v[196:199], v[32:35]
	v_mfma_f32_16x16x32_bf16 v[24:27], v[170:173], v[204:207], v[24:27]
	v_mfma_f32_16x16x32_bf16 v[16:19], v[178:181], v[204:207], v[16:19]
	v_mfma_f32_16x16x32_bf16 v[8:11], v[170:173], v[212:215], v[8:11]
	v_mfma_f32_16x16x32_bf16 v[0:3], v[178:181], v[212:215], v[0:3]
	v_mfma_f32_16x16x32_bf16 v[56:59], v[174:177], v[192:195], v[56:59]
	v_mfma_f32_16x16x32_bf16 v[48:51], v[182:185], v[192:195], v[48:51]
	v_mfma_f32_16x16x32_bf16 v[40:43], v[174:177], v[200:203], v[40:43]
	v_mfma_f32_16x16x32_bf16 v[32:35], v[182:185], v[200:203], v[32:35]
	v_mfma_f32_16x16x32_bf16 v[24:27], v[174:177], v[208:211], v[24:27]
	v_mfma_f32_16x16x32_bf16 v[16:19], v[182:185], v[208:211], v[16:19]
	v_mfma_f32_16x16x32_bf16 v[8:11], v[174:177], v[216:219], v[8:11]
	v_mfma_f32_16x16x32_bf16 v[0:3], v[182:185], v[216:219], v[0:3]
	s_barrier
	s_add_i32 s61, s61, 2
	s_add_u32 s22, s22, 0x100
	s_addc_u32 s23, s23, 0
	s_add_u32 s59, s59, 0x100
	s_addc_u32 s60, s60, 0
	s_cmp_gt_u32 s61, 13
	s_cbranch_scc1 .LBB0_1074

.LBB0_1152:
	ds_read_b128 v[128:131], v179
	ds_read_b128 v[132:135], v179 offset:1024
	ds_read_b128 v[136:139], v179 offset:2048
	ds_read_b128 v[140:143], v179 offset:3072
	ds_read_b128 v[144:147], v180
	ds_read_b128 v[148:151], v180 offset:1024
	ds_read_b128 v[164:167], v180 offset:2048
	ds_read_b128 v[168:171], v180 offset:3072
	s_add_u32 s14, s12, 0xfff50080
	s_addc_u32 s15, s13, -1
	s_cmp_eq_u32 s41, 40
	s_cselect_b32 s17, s3, s15
	s_cselect_b32 s16, s2, s14
	s_cselect_b32 s15, s11, s40
	s_cselect_b32 s14, s10, s39
	v_lshl_add_u64 v[172:173], s[12:13], 0, v[156:157]
	s_add_i32 m0, s22, 0xc000
	ds_read_b128 v[182:185], v181
	ds_read_b128 v[186:189], v181 offset:1024
	ds_read_b128 v[190:193], v181 offset:2048
	ds_read_b128 v[194:197], v181 offset:3072
	ds_read_b128 v[198:201], v181 offset:4096
	ds_read_b128 v[202:205], v181 offset:5120
	ds_read_b128 v[206:209], v181 offset:6144
	ds_read_b128 v[210:213], v181 offset:7168
	global_load_lds_dwordx4 v[172:173], off
	v_lshl_add_u64 v[172:173], s[12:13], 0, v[158:159]
	s_add_i32 m0, s22, 0xe000
	s_nop 0
	global_load_lds_dwordx4 v[172:173], off
	s_waitcnt vmcnt(8)
	s_waitcnt lgkmcnt(0)
	s_barrier
	s_waitcnt lgkmcnt(0)
	v_mfma_f32_16x16x32_bf16 v[124:127], v[128:131], v[182:185], v[124:127]
	v_mfma_f32_16x16x32_bf16 v[120:123], v[136:139], v[182:185], v[120:123]
	v_mfma_f32_16x16x32_bf16 v[116:119], v[128:131], v[190:193], v[116:119]
	v_mfma_f32_16x16x32_bf16 v[112:115], v[136:139], v[190:193], v[112:115]
	v_mfma_f32_16x16x32_bf16 v[100:103], v[128:131], v[198:201], v[100:103]
	v_mfma_f32_16x16x32_bf16 v[88:91], v[136:139], v[198:201], v[88:91]
	v_mfma_f32_16x16x32_bf16 v[84:87], v[128:131], v[206:209], v[84:87]
	v_mfma_f32_16x16x32_bf16 v[76:79], v[136:139], v[206:209], v[76:79]
	v_mfma_f32_16x16x32_bf16 v[124:127], v[132:135], v[186:189], v[124:127]
	v_mfma_f32_16x16x32_bf16 v[120:123], v[140:143], v[186:189], v[120:123]
	v_mfma_f32_16x16x32_bf16 v[116:119], v[132:135], v[194:197], v[116:119]
	v_mfma_f32_16x16x32_bf16 v[112:115], v[140:143], v[194:197], v[112:115]
	v_mfma_f32_16x16x32_bf16 v[100:103], v[132:135], v[202:205], v[100:103]
	v_mfma_f32_16x16x32_bf16 v[88:91], v[140:143], v[202:205], v[88:91]
	v_mfma_f32_16x16x32_bf16 v[84:87], v[132:135], v[210:213], v[84:87]
	v_mfma_f32_16x16x32_bf16 v[76:79], v[140:143], v[210:213], v[76:79]
	v_mfma_f32_16x16x32_bf16 v[108:111], v[144:147], v[182:185], v[108:111]
	v_mfma_f32_16x16x32_bf16 v[104:107], v[164:167], v[182:185], v[104:107]
	v_mfma_f32_16x16x32_bf16 v[96:99], v[144:147], v[190:193], v[96:99]
	v_mfma_f32_16x16x32_bf16 v[92:95], v[164:167], v[190:193], v[92:95]
	v_mfma_f32_16x16x32_bf16 v[80:83], v[144:147], v[198:201], v[80:83]
	v_mfma_f32_16x16x32_bf16 v[72:75], v[164:167], v[198:201], v[72:75]
	v_mfma_f32_16x16x32_bf16 v[68:71], v[144:147], v[206:209], v[68:71]
	v_mfma_f32_16x16x32_bf16 v[64:67], v[164:167], v[206:209], v[64:67]
	v_mfma_f32_16x16x32_bf16 v[108:111], v[148:151], v[186:189], v[108:111]
	v_mfma_f32_16x16x32_bf16 v[104:107], v[168:171], v[186:189], v[104:107]
	v_mfma_f32_16x16x32_bf16 v[96:99], v[148:151], v[194:197], v[96:99]
	v_mfma_f32_16x16x32_bf16 v[92:95], v[168:171], v[194:197], v[92:95]
	v_mfma_f32_16x16x32_bf16 v[80:83], v[148:151], v[202:205], v[80:83]
	v_mfma_f32_16x16x32_bf16 v[72:75], v[168:171], v[202:205], v[72:75]
	v_mfma_f32_16x16x32_bf16 v[68:71], v[148:151], v[210:213], v[68:71]
	v_mfma_f32_16x16x32_bf16 v[64:67], v[168:171], v[210:213], v[64:67]
	s_barrier
	s_add_i32 s42, s33, s20
	v_lshl_add_u64 v[172:173], s[14:15], 0, v[152:153]
	s_mov_b32 m0, s42
	ds_read_b128 v[182:185], v181 offset:16384
	ds_read_b128 v[186:189], v181 offset:17408
	ds_read_b128 v[190:193], v181 offset:18432
	ds_read_b128 v[194:197], v181 offset:19456
	ds_read_b128 v[198:201], v181 offset:20480
	ds_read_b128 v[202:205], v181 offset:21504
	ds_read_b128 v[206:209], v181 offset:22528
	ds_read_b128 v[210:213], v181 offset:23552
	global_load_lds_dwordx4 v[172:173], off
	s_add_i32 m0, s42, 0x2000
	s_add_u32 s42, s14, 0xb0000
	v_lshl_add_u64 v[214:215], s[14:15], 0, v[154:155]
	s_addc_u32 s43, s15, 0
	s_add_i32 s44, s34, s20
	global_load_lds_dwordx4 v[214:215], off
	v_lshl_add_u64 v[216:217], s[42:43], 0, v[152:153]
	s_mov_b32 m0, s44
	v_lshl_add_u64 v[218:219], s[16:17], 0, v[154:155]
	global_load_lds_dwordx4 v[216:217], off
	v_lshl_add_u64 v[216:217], s[42:43], 0, v[154:155]
	s_add_i32 m0, s44, 0x2000
	s_nop 0
	global_load_lds_dwordx4 v[216:217], off
	v_lshl_add_u64 v[216:217], s[16:17], 0, v[152:153]
	s_mov_b32 m0, s22
	s_nop 0
	global_load_lds_dwordx4 v[216:217], off
	s_mov_b32 m0, s23
	s_nop 0
	global_load_lds_dwordx4 v[218:219], off
	s_waitcnt vmcnt(8)
	s_waitcnt lgkmcnt(0)
	s_barrier
	s_waitcnt lgkmcnt(0)
	v_mfma_f32_16x16x32_bf16 v[60:63], v[128:131], v[182:185], v[60:63]
	v_mfma_f32_16x16x32_bf16 v[56:59], v[136:139], v[182:185], v[56:59]
	v_mfma_f32_16x16x32_bf16 v[52:55], v[128:131], v[190:193], v[52:55]
	v_mfma_f32_16x16x32_bf16 v[48:51], v[136:139], v[190:193], v[48:51]
	v_mfma_f32_16x16x32_bf16 v[40:43], v[128:131], v[198:201], v[40:43]
	v_mfma_f32_16x16x32_bf16 v[28:31], v[136:139], v[198:201], v[28:31]
	v_mfma_f32_16x16x32_bf16 v[16:19], v[128:131], v[206:209], v[16:19]
	v_mfma_f32_16x16x32_bf16 v[8:11], v[136:139], v[206:209], v[8:11]
	v_mfma_f32_16x16x32_bf16 v[60:63], v[132:135], v[186:189], v[60:63]
	v_mfma_f32_16x16x32_bf16 v[56:59], v[140:143], v[186:189], v[56:59]
	v_mfma_f32_16x16x32_bf16 v[52:55], v[132:135], v[194:197], v[52:55]
	v_mfma_f32_16x16x32_bf16 v[48:51], v[140:143], v[194:197], v[48:51]
	v_mfma_f32_16x16x32_bf16 v[40:43], v[132:135], v[202:205], v[40:43]
	v_mfma_f32_16x16x32_bf16 v[28:31], v[140:143], v[202:205], v[28:31]
	v_mfma_f32_16x16x32_bf16 v[16:19], v[132:135], v[210:213], v[16:19]
	v_mfma_f32_16x16x32_bf16 v[8:11], v[140:143], v[210:213], v[8:11]
	v_mfma_f32_16x16x32_bf16 v[44:47], v[144:147], v[182:185], v[44:47]
	v_mfma_f32_16x16x32_bf16 v[36:39], v[164:167], v[182:185], v[36:39]
	v_mfma_f32_16x16x32_bf16 v[32:35], v[144:147], v[190:193], v[32:35]
	v_mfma_f32_16x16x32_bf16 v[24:27], v[164:167], v[190:193], v[24:27]
	v_mfma_f32_16x16x32_bf16 v[20:23], v[144:147], v[198:201], v[20:23]
	v_mfma_f32_16x16x32_bf16 v[12:15], v[164:167], v[198:201], v[12:15]
	v_mfma_f32_16x16x32_bf16 v[4:7], v[144:147], v[206:209], v[4:7]
	v_mfma_f32_16x16x32_bf16 v[0:3], v[164:167], v[206:209], v[0:3]
	v_mfma_f32_16x16x32_bf16 v[44:47], v[148:151], v[186:189], v[44:47]
	v_mfma_f32_16x16x32_bf16 v[36:39], v[168:171], v[186:189], v[36:39]
	v_mfma_f32_16x16x32_bf16 v[32:35], v[148:151], v[194:197], v[32:35]
	v_mfma_f32_16x16x32_bf16 v[24:27], v[168:171], v[194:197], v[24:27]
	v_mfma_f32_16x16x32_bf16 v[20:23], v[148:151], v[202:205], v[20:23]
	v_mfma_f32_16x16x32_bf16 v[12:15], v[168:171], v[202:205], v[12:15]
	v_mfma_f32_16x16x32_bf16 v[4:7], v[148:151], v[210:213], v[4:7]
	v_mfma_f32_16x16x32_bf16 v[0:3], v[168:171], v[210:213], v[0:3]
	s_barrier
	s_add_i32 s42, 0, 0x18000
	s_add_i32 s43, 0, 0x1c000
	v_add_u32_e32 v140, s42, v175
	v_add_u32_e32 v168, s43, v175
	ds_read_b128 v[128:131], v140
	ds_read_b128 v[132:135], v140 offset:1024
	ds_read_b128 v[136:139], v140 offset:2048
	ds_read_b128 v[140:143], v140 offset:3072
	ds_read_b128 v[144:147], v168
	ds_read_b128 v[148:151], v168 offset:1024
	ds_read_b128 v[164:167], v168 offset:2048
	ds_read_b128 v[168:171], v168 offset:3072
	s_add_u32 s16, s16, 0xb0000
	s_addc_u32 s17, s17, 0
	s_mov_b32 m0, s24
	v_lshl_add_u64 v[220:221], s[16:17], 0, v[152:153]
	ds_read_b128 v[182:185], v181 offset:32768
	ds_read_b128 v[186:189], v181 offset:33792
	ds_read_b128 v[190:193], v181 offset:34816
	ds_read_b128 v[194:197], v181 offset:35840
	ds_read_b128 v[198:201], v181 offset:36864
	ds_read_b128 v[202:205], v181 offset:37888
	ds_read_b128 v[206:209], v181 offset:38912
	ds_read_b128 v[210:213], v181 offset:39936
	global_load_lds_dwordx4 v[220:221], off
	v_lshl_add_u64 v[220:221], s[16:17], 0, v[154:155]
	s_mov_b32 m0, s25
	s_nop 0
	global_load_lds_dwordx4 v[220:221], off
	s_waitcnt vmcnt(8)
	s_waitcnt lgkmcnt(0)
	s_barrier
	s_waitcnt lgkmcnt(0)
	v_mfma_f32_16x16x32_bf16 v[124:127], v[128:131], v[182:185], v[124:127]
	v_mfma_f32_16x16x32_bf16 v[120:123], v[136:139], v[182:185], v[120:123]
	v_mfma_f32_16x16x32_bf16 v[116:119], v[128:131], v[190:193], v[116:119]
	v_mfma_f32_16x16x32_bf16 v[112:115], v[136:139], v[190:193], v[112:115]
	v_mfma_f32_16x16x32_bf16 v[100:103], v[128:131], v[198:201], v[100:103]
	v_mfma_f32_16x16x32_bf16 v[88:91], v[136:139], v[198:201], v[88:91]
	v_mfma_f32_16x16x32_bf16 v[84:87], v[128:131], v[206:209], v[84:87]
	v_mfma_f32_16x16x32_bf16 v[76:79], v[136:139], v[206:209], v[76:79]
	v_mfma_f32_16x16x32_bf16 v[124:127], v[132:135], v[186:189], v[124:127]
	v_mfma_f32_16x16x32_bf16 v[120:123], v[140:143], v[186:189], v[120:123]
	v_mfma_f32_16x16x32_bf16 v[116:119], v[132:135], v[194:197], v[116:119]
	v_mfma_f32_16x16x32_bf16 v[112:115], v[140:143], v[194:197], v[112:115]
	v_mfma_f32_16x16x32_bf16 v[100:103], v[132:135], v[202:205], v[100:103]
	v_mfma_f32_16x16x32_bf16 v[88:91], v[140:143], v[202:205], v[88:91]
	v_mfma_f32_16x16x32_bf16 v[84:87], v[132:135], v[210:213], v[84:87]
	v_mfma_f32_16x16x32_bf16 v[76:79], v[140:143], v[210:213], v[76:79]
	v_mfma_f32_16x16x32_bf16 v[108:111], v[144:147], v[182:185], v[108:111]
	v_mfma_f32_16x16x32_bf16 v[104:107], v[164:167], v[182:185], v[104:107]
	v_mfma_f32_16x16x32_bf16 v[96:99], v[144:147], v[190:193], v[96:99]
	v_mfma_f32_16x16x32_bf16 v[92:95], v[164:167], v[190:193], v[92:95]
	v_mfma_f32_16x16x32_bf16 v[80:83], v[144:147], v[198:201], v[80:83]
	v_mfma_f32_16x16x32_bf16 v[72:75], v[164:167], v[198:201], v[72:75]
	v_mfma_f32_16x16x32_bf16 v[68:71], v[144:147], v[206:209], v[68:71]
	v_mfma_f32_16x16x32_bf16 v[64:67], v[164:167], v[206:209], v[64:67]
	v_mfma_f32_16x16x32_bf16 v[108:111], v[148:151], v[186:189], v[108:111]
	v_mfma_f32_16x16x32_bf16 v[104:107], v[168:171], v[186:189], v[104:107]
	v_mfma_f32_16x16x32_bf16 v[96:99], v[148:151], v[194:197], v[96:99]
	v_mfma_f32_16x16x32_bf16 v[92:95], v[168:171], v[194:197], v[92:95]
	v_mfma_f32_16x16x32_bf16 v[80:83], v[148:151], v[202:205], v[80:83]
	v_mfma_f32_16x16x32_bf16 v[72:75], v[168:171], v[202:205], v[72:75]
	v_mfma_f32_16x16x32_bf16 v[68:71], v[148:151], v[210:213], v[68:71]
	v_mfma_f32_16x16x32_bf16 v[64:67], v[168:171], v[210:213], v[64:67]
	s_barrier
	s_add_i32 s16, s42, s20
	v_lshl_add_u64 v[172:173], v[172:173], 0, s[6:7]
	s_mov_b32 m0, s16
	ds_read_b128 v[182:185], v181 offset:49152
	ds_read_b128 v[186:189], v181 offset:50176
	ds_read_b128 v[190:193], v181 offset:51200
	ds_read_b128 v[194:197], v181 offset:52224
	ds_read_b128 v[198:201], v181 offset:53248
	ds_read_b128 v[202:205], v181 offset:54272
	ds_read_b128 v[206:209], v181 offset:55296
	ds_read_b128 v[210:213], v181 offset:56320
	global_load_lds_dwordx4 v[172:173], off
	s_add_i32 m0, s16, 0x2000
	s_add_u32 s14, s14, 0xb0080
	v_lshl_add_u64 v[172:173], v[214:215], 0, s[6:7]
	s_addc_u32 s15, s15, 0
	s_add_i32 s16, s43, s20
	global_load_lds_dwordx4 v[172:173], off
	v_lshl_add_u64 v[172:173], s[14:15], 0, v[152:153]
	s_mov_b32 m0, s16
	s_nop 0
	global_load_lds_dwordx4 v[172:173], off
	v_lshl_add_u64 v[172:173], s[14:15], 0, v[154:155]
	s_add_i32 m0, s16, 0x2000
	s_nop 0
	global_load_lds_dwordx4 v[172:173], off
	v_lshl_add_u64 v[172:173], v[216:217], 0, s[6:7]
	s_mov_b32 m0, s30
	s_nop 0
	global_load_lds_dwordx4 v[172:173], off
	v_lshl_add_u64 v[172:173], v[218:219], 0, s[6:7]
	s_mov_b32 m0, s31
	s_nop 0
	global_load_lds_dwordx4 v[172:173], off
	s_waitcnt vmcnt(8)
	s_waitcnt lgkmcnt(0)
	s_barrier
	s_waitcnt lgkmcnt(0)
	v_mfma_f32_16x16x32_bf16 v[60:63], v[128:131], v[182:185], v[60:63]
	v_mfma_f32_16x16x32_bf16 v[56:59], v[136:139], v[182:185], v[56:59]
	v_mfma_f32_16x16x32_bf16 v[52:55], v[128:131], v[190:193], v[52:55]
	v_mfma_f32_16x16x32_bf16 v[48:51], v[136:139], v[190:193], v[48:51]
	v_mfma_f32_16x16x32_bf16 v[40:43], v[128:131], v[198:201], v[40:43]
	v_mfma_f32_16x16x32_bf16 v[28:31], v[136:139], v[198:201], v[28:31]
	v_mfma_f32_16x16x32_bf16 v[16:19], v[128:131], v[206:209], v[16:19]
	v_mfma_f32_16x16x32_bf16 v[8:11], v[136:139], v[206:209], v[8:11]
	v_mfma_f32_16x16x32_bf16 v[60:63], v[132:135], v[186:189], v[60:63]
	v_mfma_f32_16x16x32_bf16 v[56:59], v[140:143], v[186:189], v[56:59]
	v_mfma_f32_16x16x32_bf16 v[52:55], v[132:135], v[194:197], v[52:55]
	v_mfma_f32_16x16x32_bf16 v[48:51], v[140:143], v[194:197], v[48:51]
	v_mfma_f32_16x16x32_bf16 v[40:43], v[132:135], v[202:205], v[40:43]
	v_mfma_f32_16x16x32_bf16 v[28:31], v[140:143], v[202:205], v[28:31]
	v_mfma_f32_16x16x32_bf16 v[16:19], v[132:135], v[210:213], v[16:19]
	v_mfma_f32_16x16x32_bf16 v[8:11], v[140:143], v[210:213], v[8:11]
	v_mfma_f32_16x16x32_bf16 v[44:47], v[144:147], v[182:185], v[44:47]
	v_mfma_f32_16x16x32_bf16 v[36:39], v[164:167], v[182:185], v[36:39]
	v_mfma_f32_16x16x32_bf16 v[32:35], v[144:147], v[190:193], v[32:35]
	v_mfma_f32_16x16x32_bf16 v[24:27], v[164:167], v[190:193], v[24:27]
	v_mfma_f32_16x16x32_bf16 v[20:23], v[144:147], v[198:201], v[20:23]
	v_mfma_f32_16x16x32_bf16 v[12:15], v[164:167], v[198:201], v[12:15]
	v_mfma_f32_16x16x32_bf16 v[4:7], v[144:147], v[206:209], v[4:7]
	v_mfma_f32_16x16x32_bf16 v[0:3], v[164:167], v[206:209], v[0:3]
	v_mfma_f32_16x16x32_bf16 v[44:47], v[148:151], v[186:189], v[44:47]
	v_mfma_f32_16x16x32_bf16 v[36:39], v[168:171], v[186:189], v[36:39]
	v_mfma_f32_16x16x32_bf16 v[32:35], v[148:151], v[194:197], v[32:35]
	v_mfma_f32_16x16x32_bf16 v[24:27], v[168:171], v[194:197], v[24:27]
	v_mfma_f32_16x16x32_bf16 v[20:23], v[148:151], v[202:205], v[20:23]
	v_mfma_f32_16x16x32_bf16 v[12:15], v[168:171], v[202:205], v[12:15]
	v_mfma_f32_16x16x32_bf16 v[4:7], v[148:151], v[210:213], v[4:7]
	v_mfma_f32_16x16x32_bf16 v[0:3], v[168:171], v[210:213], v[0:3]
	s_barrier
	s_add_i32 s41, s41, 2
	s_add_u32 s12, s12, 0x100
	s_addc_u32 s13, s13, 0
	s_add_u32 s39, s39, 0x100
	s_addc_u32 s40, s40, 0
	s_cmp_gt_u32 s41, 41
	s_cbranch_scc0 .LBB0_1152
	s_and_b64 vcc, exec, s[8:9]
	s_cbranch_vccz .LBB0_1155
	s_barrier
